# v25 plus hazard nops behind m0 writes replaced by the address add (GEMM loops) or the first V fragment reads (attention loop)
# baseline (speedup 1.0000x reference)
; #define PG8_STAGE(bufoff, gbase, voff) do { _Pragma("unroll") for (int _i = 0; _i < 2; ++_i) \
;         __builtin_amdgcn_global_load_lds((const unsigned*)((const char*)(gbase) + (voff)[_i]), (LAS unsigned*)(lds + (bufoff) + ldsw + _i * 8192), 16, 0, 0); } while (0)
; #define PG8_LDA(dst, b, h) do { _Pragma("unroll") for (int m = 0; m < 4; ++m) _Pragma("unroll") for (int k = 0; k < 2; ++k) dst[m][k] = *(const LAS bf16x8*)(lds + PG8_SA(b, h) + aoff + m * 2048 + k * 1024); } while (0)
; #define PG8_LDB(dst, b, h) do { _Pragma("unroll") for (int n = 0; n < 2; ++n) _Pragma("unroll") for (int k = 0; k < 2; ++k) dst[n][k] = *(const LAS bf16x8*)(lds + PG8_SB(b, h) + boff + n * 2048 + k * 1024); } while (0)
; #define PG8_MMA(ai, bj, At, Bt) do { __builtin_amdgcn_s_setprio(1); _Pragma("unroll") for (int m = 0; m < 4; ++m) _Pragma("unroll") for (int n = 0; n < 2; ++n) _Pragma("unroll") for (int k = 0; k < 2; ++k) \
;         acc[ai][bj][m][n] = __builtin_amdgcn_mfma_f32_16x16x32_bf16(Bt[n][k], At[m][k], acc[ai][bj][m][n], 0, 0, 0); __builtin_amdgcn_s_setprio(0); } while (0)
; #define PG8_WAIT_V(n) asm volatile("s_waitcnt vmcnt(" #n ")" ::: "memory")
; #define PG8_WAIT_L(n) asm volatile("s_waitcnt lgkmcnt(" #n ")" ::: "memory")
; #define PG8_BAR __builtin_amdgcn_s_barrier()
; #define PG8_SCHED __builtin_amdgcn_sched_barrier(0)
; template <class Epi, class Sched>
; __device__ __forceinline__ void gemm_phase(LAS unsigned char* lds, const Gemm g, const Sched& S, const Epi& E, const int wid) {
;     ...
;             const bool last = (t == nt - 2);
;             const char* a1 = cA + (size_t)(t + 1) * kstep;
;             const char* a2 = last ? nA : cA + (size_t)(t + 2) * kstep; const char* b2 = last ? nB : cB + (size_t)(t + 2) * kstep;
;             const char* a3 = a2 + kstep; const char* b3 = b2 + kstep;
;             PG8_LDB(B0, 0, 0); PG8_LDB(B1, 0, 1); PG8_SCHED; PG8_LDA(At, 0, 0); PG8_STAGE(PG8_SA(1, 1), a1 + hstepA, voffA);
;             PG8_WAIT_V(8); PG8_WAIT_L(0); PG8_BAR; PG8_MMA(0, 0, At, B0); PG8_MMA(0, 1, At, B1); PG8_BAR; PG8_SCHED;
;             PG8_LDA(At, 0, 1); PG8_STAGE(PG8_SB(0, 0), b2, voffB); PG8_STAGE(PG8_SB(0, 1), b2 + hstepB, voffB); PG8_STAGE(PG8_SA(0, 0), a2, voffA);
;             PG8_WAIT_V(8); PG8_WAIT_L(0); PG8_BAR; PG8_MMA(1, 0, At, B0); PG8_MMA(1, 1, At, B1); PG8_BAR; PG8_SCHED;
.LBB0_247:
	v_add_u32_e32 v144, s76, v171
	ds_read_b128 v[128:131], v144
	ds_read_b128 v[132:135], v144 offset:1024
	ds_read_b128 v[192:195], v144 offset:2048
	ds_read_b128 v[196:199], v144 offset:3072
	v_add_u32_e32 v144, s77, v171
	ds_read_b128 v[200:203], v144
	ds_read_b128 v[204:207], v144 offset:1024
	ds_read_b128 v[208:211], v144 offset:2048
	ds_read_b128 v[212:215], v144 offset:3072
	s_add_u32 s58, s56, 0xfffc0080
	s_addc_u32 s59, s57, -1
	s_cmp_eq_u32 s86, 12
	s_cselect_b32 s61, s16, s59
	s_cselect_b32 s60, s47, s58
	s_cselect_b32 s59, s45, s85
	s_cselect_b32 s58, s53, s84
	v_lshl_add_u64 v[168:169], s[56:57], 0, v[160:161]
	s_add_i32 m0, s55, 0xc000
	ds_read_b128 v[216:219], v188
	ds_read_b128 v[220:223], v188 offset:1024
	ds_read_b128 v[224:227], v188 offset:2048
	ds_read_b128 v[228:231], v188 offset:3072
	ds_read_b128 v[232:235], v188 offset:4096
	ds_read_b128 v[236:239], v188 offset:5120
	ds_read_b128 v[240:243], v188 offset:6144
	ds_read_b128 v[244:247], v188 offset:7168
	global_load_lds_dwordx4 v[168:169], off
	s_add_i32 m0, s55, 0xe000
	v_lshl_add_u64 v[168:169], s[56:57], 0, v[162:163]
	global_load_lds_dwordx4 v[168:169], off
	s_waitcnt vmcnt(8)
	s_waitcnt lgkmcnt(0)
	s_barrier
	s_setprio 1
	v_mfma_f32_16x16x32_bf16 v[124:127], v[128:131], v[216:219], v[124:127]
	v_mfma_f32_16x16x32_bf16 v[120:123], v[192:195], v[216:219], v[120:123]
	v_mfma_f32_16x16x32_bf16 v[108:111], v[128:131], v[224:227], v[108:111]
	v_mfma_f32_16x16x32_bf16 v[104:107], v[192:195], v[224:227], v[104:107]
	v_mfma_f32_16x16x32_bf16 v[92:95], v[128:131], v[232:235], v[92:95]
	v_mfma_f32_16x16x32_bf16 v[88:91], v[192:195], v[232:235], v[88:91]
	v_mfma_f32_16x16x32_bf16 v[76:79], v[128:131], v[240:243], v[76:79]
	v_mfma_f32_16x16x32_bf16 v[72:75], v[192:195], v[240:243], v[72:75]
	v_mfma_f32_16x16x32_bf16 v[124:127], v[132:135], v[220:223], v[124:127]
	v_mfma_f32_16x16x32_bf16 v[120:123], v[196:199], v[220:223], v[120:123]
	v_mfma_f32_16x16x32_bf16 v[108:111], v[132:135], v[228:231], v[108:111]
	v_mfma_f32_16x16x32_bf16 v[104:107], v[196:199], v[228:231], v[104:107]
	v_mfma_f32_16x16x32_bf16 v[92:95], v[132:135], v[236:239], v[92:95]
	v_mfma_f32_16x16x32_bf16 v[88:91], v[196:199], v[236:239], v[88:91]
	v_mfma_f32_16x16x32_bf16 v[76:79], v[132:135], v[244:247], v[76:79]
	v_mfma_f32_16x16x32_bf16 v[72:75], v[196:199], v[244:247], v[72:75]
	v_mfma_f32_16x16x32_bf16 v[116:119], v[200:203], v[216:219], v[116:119]
	v_mfma_f32_16x16x32_bf16 v[112:115], v[208:211], v[216:219], v[112:115]
	v_mfma_f32_16x16x32_bf16 v[100:103], v[200:203], v[224:227], v[100:103]
	v_mfma_f32_16x16x32_bf16 v[96:99], v[208:211], v[224:227], v[96:99]
	v_mfma_f32_16x16x32_bf16 v[84:87], v[200:203], v[232:235], v[84:87]
	v_mfma_f32_16x16x32_bf16 v[80:83], v[208:211], v[232:235], v[80:83]
	v_mfma_f32_16x16x32_bf16 v[68:71], v[200:203], v[240:243], v[68:71]
	v_mfma_f32_16x16x32_bf16 v[64:67], v[208:211], v[240:243], v[64:67]
	v_mfma_f32_16x16x32_bf16 v[116:119], v[204:207], v[220:223], v[116:119]
	v_mfma_f32_16x16x32_bf16 v[112:115], v[212:215], v[220:223], v[112:115]
	v_mfma_f32_16x16x32_bf16 v[100:103], v[204:207], v[228:231], v[100:103]
	v_mfma_f32_16x16x32_bf16 v[96:99], v[212:215], v[228:231], v[96:99]
	v_mfma_f32_16x16x32_bf16 v[84:87], v[204:207], v[236:239], v[84:87]
	v_mfma_f32_16x16x32_bf16 v[80:83], v[212:215], v[236:239], v[80:83]
	v_mfma_f32_16x16x32_bf16 v[68:71], v[204:207], v[244:247], v[68:71]
	v_mfma_f32_16x16x32_bf16 v[64:67], v[212:215], v[244:247], v[64:67]
	s_setprio 0
	s_barrier
	s_add_i32 s87, s76, s65
	v_lshl_add_u64 v[168:169], s[58:59], 0, v[138:139]
	s_mov_b32 m0, s87
	ds_read_b128 v[216:219], v188 offset:16384
	ds_read_b128 v[220:223], v188 offset:17408
	ds_read_b128 v[224:227], v188 offset:18432
	ds_read_b128 v[228:231], v188 offset:19456
	ds_read_b128 v[232:235], v188 offset:20480
	ds_read_b128 v[236:239], v188 offset:21504
	ds_read_b128 v[240:243], v188 offset:22528
	ds_read_b128 v[244:247], v188 offset:23552
	global_load_lds_dwordx4 v[168:169], off
	s_add_i32 m0, s87, 0x2000
	s_add_u32 s88, s58, 0x40000
	v_lshl_add_u64 v[248:249], s[58:59], 0, v[142:143]
	s_addc_u32 s89, s59, 0
	s_add_i32 s87, s77, s65
	global_load_lds_dwordx4 v[248:249], off
	v_lshl_add_u64 v[250:251], s[88:89], 0, v[138:139]
	s_mov_b32 m0, s87
	v_lshl_add_u64 v[252:253], s[60:61], 0, v[140:141]
	global_load_lds_dwordx4 v[250:251], off
	s_add_i32 m0, s87, 0x2000
	v_lshl_add_u64 v[250:251], s[88:89], 0, v[142:143]
	global_load_lds_dwordx4 v[250:251], off
	s_mov_b32 m0, s55
	v_lshl_add_u64 v[250:251], s[60:61], 0, v[136:137]
	global_load_lds_dwordx4 v[250:251], off
	s_mov_b32 m0, s66
	s_nop 0
	global_load_lds_dwordx4 v[252:253], off
	s_waitcnt vmcnt(8)
	s_waitcnt lgkmcnt(0)
	s_barrier
; #define PG8_STAGE(bufoff, gbase, voff) do { _Pragma("unroll") for (int _i = 0; _i < 2; ++_i) \
;         __builtin_amdgcn_global_load_lds((const unsigned*)((const char*)(gbase) + (voff)[_i]), (LAS unsigned*)(lds + (bufoff) + ldsw + _i * 8192), 16, 0, 0); } while (0)
; #define PG8_LDA(dst, b, h) do { _Pragma("unroll") for (int m = 0; m < 4; ++m) _Pragma("unroll") for (int k = 0; k < 2; ++k) dst[m][k] = *(const LAS bf16x8*)(lds + PG8_SA(b, h) + aoff + m * 2048 + k * 1024); } while (0)
; #define PG8_LDB(dst, b, h) do { _Pragma("unroll") for (int n = 0; n < 2; ++n) _Pragma("unroll") for (int k = 0; k < 2; ++k) dst[n][k] = *(const LAS bf16x8*)(lds + PG8_SB(b, h) + boff + n * 2048 + k * 1024); } while (0)
; #define PG8_MMA(ai, bj, At, Bt) do { __builtin_amdgcn_s_setprio(1); _Pragma("unroll") for (int m = 0; m < 4; ++m) _Pragma("unroll") for (int n = 0; n < 2; ++n) _Pragma("unroll") for (int k = 0; k < 2; ++k) \
;         acc[ai][bj][m][n] = __builtin_amdgcn_mfma_f32_16x16x32_bf16(Bt[n][k], At[m][k], acc[ai][bj][m][n], 0, 0, 0); __builtin_amdgcn_s_setprio(0); } while (0)
; #define PG8_WAIT_V(n) asm volatile("s_waitcnt vmcnt(" #n ")" ::: "memory")
; #define PG8_WAIT_L(n) asm volatile("s_waitcnt lgkmcnt(" #n ")" ::: "memory")
; #define PG8_BAR __builtin_amdgcn_s_barrier()
; #define PG8_SCHED __builtin_amdgcn_sched_barrier(0)
; template <class Epi, class Sched>
; __device__ __forceinline__ void gemm_phase(LAS unsigned char* lds, const Gemm g, const Sched& S, const Epi& E, const int wid) {
;     ...
;             PG8_WAIT_V(8); PG8_WAIT_L(0); PG8_BAR; PG8_MMA(1, 0, At, B0); PG8_MMA(1, 1, At, B1); PG8_BAR; PG8_SCHED;
;             PG8_LDB(B0, 1, 0); PG8_LDB(B1, 1, 1); PG8_SCHED; PG8_LDA(At, 1, 0); PG8_STAGE(PG8_SA(0, 1), a2 + hstepA, voffA);
;             PG8_WAIT_V(8); PG8_WAIT_L(0); PG8_BAR; PG8_MMA(0, 0, At, B0); PG8_MMA(0, 1, At, B1); PG8_BAR; PG8_SCHED;
	s_setprio 1
	v_mfma_f32_16x16x32_bf16 v[60:63], v[128:131], v[216:219], v[60:63]
	v_mfma_f32_16x16x32_bf16 v[56:59], v[192:195], v[216:219], v[56:59]
	v_mfma_f32_16x16x32_bf16 v[44:47], v[128:131], v[224:227], v[44:47]
	v_mfma_f32_16x16x32_bf16 v[40:43], v[192:195], v[224:227], v[40:43]
	v_mfma_f32_16x16x32_bf16 v[28:31], v[128:131], v[232:235], v[28:31]
	v_mfma_f32_16x16x32_bf16 v[24:27], v[192:195], v[232:235], v[24:27]
	v_mfma_f32_16x16x32_bf16 v[12:15], v[128:131], v[240:243], v[12:15]
	v_mfma_f32_16x16x32_bf16 v[8:11], v[192:195], v[240:243], v[8:11]
	v_mfma_f32_16x16x32_bf16 v[60:63], v[132:135], v[220:223], v[60:63]
	v_mfma_f32_16x16x32_bf16 v[56:59], v[196:199], v[220:223], v[56:59]
	v_mfma_f32_16x16x32_bf16 v[44:47], v[132:135], v[228:231], v[44:47]
	v_mfma_f32_16x16x32_bf16 v[40:43], v[196:199], v[228:231], v[40:43]
	v_mfma_f32_16x16x32_bf16 v[28:31], v[132:135], v[236:239], v[28:31]
	v_mfma_f32_16x16x32_bf16 v[24:27], v[196:199], v[236:239], v[24:27]
	v_mfma_f32_16x16x32_bf16 v[12:15], v[132:135], v[244:247], v[12:15]
	v_mfma_f32_16x16x32_bf16 v[8:11], v[196:199], v[244:247], v[8:11]
	v_mfma_f32_16x16x32_bf16 v[52:55], v[200:203], v[216:219], v[52:55]
	v_mfma_f32_16x16x32_bf16 v[48:51], v[208:211], v[216:219], v[48:51]
	v_mfma_f32_16x16x32_bf16 v[36:39], v[200:203], v[224:227], v[36:39]
	v_mfma_f32_16x16x32_bf16 v[32:35], v[208:211], v[224:227], v[32:35]
	v_mfma_f32_16x16x32_bf16 v[20:23], v[200:203], v[232:235], v[20:23]
	v_mfma_f32_16x16x32_bf16 v[16:19], v[208:211], v[232:235], v[16:19]
	v_mfma_f32_16x16x32_bf16 v[4:7], v[200:203], v[240:243], v[4:7]
	v_mfma_f32_16x16x32_bf16 v[0:3], v[208:211], v[240:243], v[0:3]
	v_mfma_f32_16x16x32_bf16 v[52:55], v[204:207], v[220:223], v[52:55]
	v_mfma_f32_16x16x32_bf16 v[48:51], v[212:215], v[220:223], v[48:51]
	v_mfma_f32_16x16x32_bf16 v[36:39], v[204:207], v[228:231], v[36:39]
	v_mfma_f32_16x16x32_bf16 v[32:35], v[212:215], v[228:231], v[32:35]
	v_mfma_f32_16x16x32_bf16 v[20:23], v[204:207], v[236:239], v[20:23]
	v_mfma_f32_16x16x32_bf16 v[16:19], v[212:215], v[236:239], v[16:19]
	v_mfma_f32_16x16x32_bf16 v[4:7], v[204:207], v[244:247], v[4:7]
	v_mfma_f32_16x16x32_bf16 v[0:3], v[212:215], v[244:247], v[0:3]
	s_setprio 0
	s_barrier
	s_add_i32 s87, 0, 0x18000
	v_add_u32_e32 v144, s87, v171
	s_add_i32 s88, 0, 0x1c000
	ds_read_b128 v[128:131], v144
	ds_read_b128 v[132:135], v144 offset:1024
	ds_read_b128 v[192:195], v144 offset:2048
	ds_read_b128 v[196:199], v144 offset:3072
	v_add_u32_e32 v144, s88, v171
	ds_read_b128 v[200:203], v144
	ds_read_b128 v[204:207], v144 offset:1024
	ds_read_b128 v[208:211], v144 offset:2048
	ds_read_b128 v[212:215], v144 offset:3072
	s_add_u32 s60, s60, 0x40000
	s_addc_u32 s61, s61, 0
	s_mov_b32 m0, s67
	v_lshl_add_u64 v[254:255], s[60:61], 0, v[136:137]
	ds_read_b128 v[216:219], v188 offset:32768
	ds_read_b128 v[220:223], v188 offset:33792
	ds_read_b128 v[224:227], v188 offset:34816
	ds_read_b128 v[228:231], v188 offset:35840
	ds_read_b128 v[232:235], v188 offset:36864
	ds_read_b128 v[236:239], v188 offset:37888
	ds_read_b128 v[240:243], v188 offset:38912
	ds_read_b128 v[244:247], v188 offset:39936
	global_load_lds_dwordx4 v[254:255], off
	s_mov_b32 m0, s68
	v_lshl_add_u64 v[254:255], s[60:61], 0, v[140:141]
	global_load_lds_dwordx4 v[254:255], off
	s_waitcnt vmcnt(8)
	s_waitcnt lgkmcnt(0)
	s_barrier
	s_setprio 1
	v_mfma_f32_16x16x32_bf16 v[124:127], v[128:131], v[216:219], v[124:127]
	v_mfma_f32_16x16x32_bf16 v[120:123], v[192:195], v[216:219], v[120:123]
	v_mfma_f32_16x16x32_bf16 v[108:111], v[128:131], v[224:227], v[108:111]
	v_mfma_f32_16x16x32_bf16 v[104:107], v[192:195], v[224:227], v[104:107]
	v_mfma_f32_16x16x32_bf16 v[92:95], v[128:131], v[232:235], v[92:95]
	v_mfma_f32_16x16x32_bf16 v[88:91], v[192:195], v[232:235], v[88:91]
	v_mfma_f32_16x16x32_bf16 v[76:79], v[128:131], v[240:243], v[76:79]
	v_mfma_f32_16x16x32_bf16 v[72:75], v[192:195], v[240:243], v[72:75]
	v_mfma_f32_16x16x32_bf16 v[124:127], v[132:135], v[220:223], v[124:127]
	v_mfma_f32_16x16x32_bf16 v[120:123], v[196:199], v[220:223], v[120:123]
	v_mfma_f32_16x16x32_bf16 v[108:111], v[132:135], v[228:231], v[108:111]
	v_mfma_f32_16x16x32_bf16 v[104:107], v[196:199], v[228:231], v[104:107]
	v_mfma_f32_16x16x32_bf16 v[92:95], v[132:135], v[236:239], v[92:95]
	v_mfma_f32_16x16x32_bf16 v[88:91], v[196:199], v[236:239], v[88:91]
	v_mfma_f32_16x16x32_bf16 v[76:79], v[132:135], v[244:247], v[76:79]
	v_mfma_f32_16x16x32_bf16 v[72:75], v[196:199], v[244:247], v[72:75]
	v_mfma_f32_16x16x32_bf16 v[116:119], v[200:203], v[216:219], v[116:119]
	v_mfma_f32_16x16x32_bf16 v[112:115], v[208:211], v[216:219], v[112:115]
	v_mfma_f32_16x16x32_bf16 v[100:103], v[200:203], v[224:227], v[100:103]
	v_mfma_f32_16x16x32_bf16 v[96:99], v[208:211], v[224:227], v[96:99]
	v_mfma_f32_16x16x32_bf16 v[84:87], v[200:203], v[232:235], v[84:87]
	v_mfma_f32_16x16x32_bf16 v[80:83], v[208:211], v[232:235], v[80:83]
	v_mfma_f32_16x16x32_bf16 v[68:71], v[200:203], v[240:243], v[68:71]
	v_mfma_f32_16x16x32_bf16 v[64:67], v[208:211], v[240:243], v[64:67]
	v_mfma_f32_16x16x32_bf16 v[116:119], v[204:207], v[220:223], v[116:119]
	v_mfma_f32_16x16x32_bf16 v[112:115], v[212:215], v[220:223], v[112:115]
	v_mfma_f32_16x16x32_bf16 v[100:103], v[204:207], v[228:231], v[100:103]
	v_mfma_f32_16x16x32_bf16 v[96:99], v[212:215], v[228:231], v[96:99]
	v_mfma_f32_16x16x32_bf16 v[84:87], v[204:207], v[236:239], v[84:87]
	v_mfma_f32_16x16x32_bf16 v[80:83], v[212:215], v[236:239], v[80:83]
	v_mfma_f32_16x16x32_bf16 v[68:71], v[204:207], v[244:247], v[68:71]
	v_mfma_f32_16x16x32_bf16 v[64:67], v[212:215], v[244:247], v[64:67]
	s_setprio 0
	s_barrier
; #define PG8_STAGE(bufoff, gbase, voff) do { _Pragma("unroll") for (int _i = 0; _i < 2; ++_i) \
;         __builtin_amdgcn_global_load_lds((const unsigned*)((const char*)(gbase) + (voff)[_i]), (LAS unsigned*)(lds + (bufoff) + ldsw + _i * 8192), 16, 0, 0); } while (0)
; #define PG8_LDA(dst, b, h) do { _Pragma("unroll") for (int m = 0; m < 4; ++m) _Pragma("unroll") for (int k = 0; k < 2; ++k) dst[m][k] = *(const LAS bf16x8*)(lds + PG8_SA(b, h) + aoff + m * 2048 + k * 1024); } while (0)
; #define PG8_MMA(ai, bj, At, Bt) do { __builtin_amdgcn_s_setprio(1); _Pragma("unroll") for (int m = 0; m < 4; ++m) _Pragma("unroll") for (int n = 0; n < 2; ++n) _Pragma("unroll") for (int k = 0; k < 2; ++k) \
;         acc[ai][bj][m][n] = __builtin_amdgcn_mfma_f32_16x16x32_bf16(Bt[n][k], At[m][k], acc[ai][bj][m][n], 0, 0, 0); __builtin_amdgcn_s_setprio(0); } while (0)
; #define PG8_WAIT_V(n) asm volatile("s_waitcnt vmcnt(" #n ")" ::: "memory")
; #define PG8_WAIT_L(n) asm volatile("s_waitcnt lgkmcnt(" #n ")" ::: "memory")
; #define PG8_BAR __builtin_amdgcn_s_barrier()
; #define PG8_SCHED __builtin_amdgcn_sched_barrier(0)
;     __device__ __forceinline__ void operator()(const f32x4 (&acc)[2][2][4][2], const Unit& u, int wr, int wc, int fr, int fq) const {
;     ...
;         if (u.pn <= 4) {
; template <class Epi, class Sched>
; __device__ __forceinline__ void gemm_phase(LAS unsigned char* lds, const Gemm g, const Sched& S, const Epi& E, const int wid) {
;     ...
;             PG8_LDA(At, 1, 1); PG8_STAGE(PG8_SB(1, 0), b3, voffB); PG8_STAGE(PG8_SB(1, 1), b3 + hstepB, voffB); PG8_STAGE(PG8_SA(1, 0), a3, voffA);
;             PG8_WAIT_V(8); PG8_WAIT_L(0); PG8_BAR; PG8_MMA(1, 0, At, B0); PG8_MMA(1, 1, At, B1); PG8_BAR; PG8_SCHED;
;         }
;         if (wr == 0) PG8_BAR;
	s_add_i32 s60, s87, s65
	v_lshl_add_u64 v[168:169], v[168:169], 0, s[22:23]
	s_mov_b32 m0, s60
	ds_read_b128 v[216:219], v188 offset:49152
	ds_read_b128 v[220:223], v188 offset:50176
	ds_read_b128 v[224:227], v188 offset:51200
	ds_read_b128 v[228:231], v188 offset:52224
	ds_read_b128 v[232:235], v188 offset:53248
	ds_read_b128 v[236:239], v188 offset:54272
	ds_read_b128 v[240:243], v188 offset:55296
	ds_read_b128 v[244:247], v188 offset:56320
	global_load_lds_dwordx4 v[168:169], off
	s_add_i32 m0, s60, 0x2000
	s_add_u32 s58, s58, 0x40080
	v_lshl_add_u64 v[168:169], v[248:249], 0, s[22:23]
	s_addc_u32 s59, s59, 0
	s_add_i32 s60, s88, s65
	global_load_lds_dwordx4 v[168:169], off
	s_mov_b32 m0, s60
	v_lshl_add_u64 v[168:169], s[58:59], 0, v[138:139]
	global_load_lds_dwordx4 v[168:169], off
	s_add_i32 m0, s60, 0x2000
	v_lshl_add_u64 v[168:169], s[58:59], 0, v[142:143]
	global_load_lds_dwordx4 v[168:169], off
	s_mov_b32 m0, s70
	v_lshl_add_u64 v[168:169], v[250:251], 0, s[22:23]
	global_load_lds_dwordx4 v[168:169], off
	s_mov_b32 m0, s71
	v_lshl_add_u64 v[168:169], v[252:253], 0, s[22:23]
	global_load_lds_dwordx4 v[168:169], off
	s_waitcnt vmcnt(8)
	s_waitcnt lgkmcnt(0)
	s_barrier
	s_setprio 1
	v_mfma_f32_16x16x32_bf16 v[60:63], v[128:131], v[216:219], v[60:63]
	v_mfma_f32_16x16x32_bf16 v[56:59], v[192:195], v[216:219], v[56:59]
	v_mfma_f32_16x16x32_bf16 v[44:47], v[128:131], v[224:227], v[44:47]
	v_mfma_f32_16x16x32_bf16 v[40:43], v[192:195], v[224:227], v[40:43]
	v_mfma_f32_16x16x32_bf16 v[28:31], v[128:131], v[232:235], v[28:31]
	v_mfma_f32_16x16x32_bf16 v[24:27], v[192:195], v[232:235], v[24:27]
	v_mfma_f32_16x16x32_bf16 v[12:15], v[128:131], v[240:243], v[12:15]
	v_mfma_f32_16x16x32_bf16 v[8:11], v[192:195], v[240:243], v[8:11]
	v_mfma_f32_16x16x32_bf16 v[60:63], v[132:135], v[220:223], v[60:63]
	v_mfma_f32_16x16x32_bf16 v[56:59], v[196:199], v[220:223], v[56:59]
	v_mfma_f32_16x16x32_bf16 v[44:47], v[132:135], v[228:231], v[44:47]
	v_mfma_f32_16x16x32_bf16 v[40:43], v[196:199], v[228:231], v[40:43]
	v_mfma_f32_16x16x32_bf16 v[28:31], v[132:135], v[236:239], v[28:31]
	v_mfma_f32_16x16x32_bf16 v[24:27], v[196:199], v[236:239], v[24:27]
	v_mfma_f32_16x16x32_bf16 v[12:15], v[132:135], v[244:247], v[12:15]
	v_mfma_f32_16x16x32_bf16 v[8:11], v[196:199], v[244:247], v[8:11]
	v_mfma_f32_16x16x32_bf16 v[52:55], v[200:203], v[216:219], v[52:55]
	v_mfma_f32_16x16x32_bf16 v[48:51], v[208:211], v[216:219], v[48:51]
	v_mfma_f32_16x16x32_bf16 v[36:39], v[200:203], v[224:227], v[36:39]
	v_mfma_f32_16x16x32_bf16 v[32:35], v[208:211], v[224:227], v[32:35]
	v_mfma_f32_16x16x32_bf16 v[20:23], v[200:203], v[232:235], v[20:23]
	v_mfma_f32_16x16x32_bf16 v[16:19], v[208:211], v[232:235], v[16:19]
	v_mfma_f32_16x16x32_bf16 v[4:7], v[200:203], v[240:243], v[4:7]
	v_mfma_f32_16x16x32_bf16 v[0:3], v[208:211], v[240:243], v[0:3]
	v_mfma_f32_16x16x32_bf16 v[52:55], v[204:207], v[220:223], v[52:55]
	v_mfma_f32_16x16x32_bf16 v[48:51], v[212:215], v[220:223], v[48:51]
	v_mfma_f32_16x16x32_bf16 v[36:39], v[204:207], v[228:231], v[36:39]
	v_mfma_f32_16x16x32_bf16 v[32:35], v[212:215], v[228:231], v[32:35]
	v_mfma_f32_16x16x32_bf16 v[20:23], v[204:207], v[236:239], v[20:23]
	v_mfma_f32_16x16x32_bf16 v[16:19], v[212:215], v[236:239], v[16:19]
	v_mfma_f32_16x16x32_bf16 v[4:7], v[204:207], v[244:247], v[4:7]
	v_mfma_f32_16x16x32_bf16 v[0:3], v[212:215], v[244:247], v[0:3]
	s_setprio 0
	s_barrier
	s_add_i32 s86, s86, 2
	s_add_u32 s56, s56, 0x100
	s_addc_u32 s57, s57, 0
	s_add_u32 s84, s84, 0x100
	s_addc_u32 s85, s85, 0
	s_cmp_gt_u32 s86, 13
	s_cbranch_scc0 .LBB0_247
	s_and_b64 vcc, exec, s[34:35]
	s_cbranch_vccnz .LBB0_252
	s_cmp_gt_i32 s54, 4
	s_mov_b64 s[56:57], -1
	s_cbranch_scc1 .LBB0_253

; #define DMA(slot, t) do { \
;     __builtin_amdgcn_global_load_lds((const unsigned*)(Kg + (long)(t) * (64 * 256)), (LAS unsigned*)(L3 + K_OFF + (slot) * SHM_T + wid * 1024), 16, 0, 0); \
;     __builtin_amdgcn_global_load_lds((const unsigned*)(Vg + (long)(t) * 8192), (LAS unsigned*)(L3 + (slot) * SHM_T + wid * 1024), 16, 0, 0); } while (0)
; #define BAR() do { asm volatile("s_waitcnt lgkmcnt(0)" ::: "memory"); __builtin_amdgcn_s_barrier(); asm volatile("" ::: "memory"); } while (0)
; #define WAITV(n) asm volatile("s_waitcnt vmcnt(" #n ")" ::: "memory")
; #define QKT(P0, P1, b) qkt(P0, P1, nm, K_lds + (b) * SHM_T, qr, ko, c00, c01, c10, c11)
; #define lane lane_id()
; __device__ __forceinline__ void body(const unsigned char* Q8b, const unsigned char* K8h, const unsigned char* VT8h, const bf16_t* Gb, bf16_t* Ob, int seq, char* lds, const int wid, ...
;     ...
;   const int krow = wid * 8 + (lane >> 3), kc = (lane & 7) ^ ((krow >> 1) & 7);
;   const char* Kg = (const char*)K8h + krow * 256 + kc * 16; const char* Vg = (const char*)VT8h + wid * 1024 + lane * 16;
;   const int ksw = (r32 >> 1) & 7, ko = r32 * 128, c00 = ((0 + hi * 2) ^ ksw) << 4, c01 = ((1 + hi * 2) ^ ksw) << 4, c10 = ((4 + hi * 2) ^ ksw) << 4, c11 = ((5 + hi * 2) ^ ksw) << 4;
;   const int vsw = (r32 >> 2) & 3, vo = r32 * 64, e0 = ((2 * hi) ^ vsw) << 4, e1 = ((2 * hi + 1) ^ vsw) << 4;
;     ...
;   f32x16 pA0, pA1, pB0, pB1; float alA, alB; v8i pf; v8i vf[4]; const int NT = seq / KVBLK;
;   if (!pre) { DMA(0, 0); DMA(1, 1); } else BAR();
;   DMA(2, 2);
;   WAITV(2); BAR();
;   QKT(pA0, pA1, 0); partialSM_first(pA0, pA1, nm);
.LBB0_369:
	s_lshl_b32 s47, s50, 1
	s_add_i32 s58, s47, s45
	s_ashr_i32 s59, s58, 31
	s_lshl_b64 s[58:59], s[58:59], 20
	v_lshl_add_u64 v[2:3], s[48:49], 0, v[202:203]
	v_lshl_add_u64 v[220:221], v[2:3], 0, v[204:205]
	s_andn2_b64 vcc, exec, s[60:61]
	v_lshl_add_u64 v[222:223], v[206:207], 0, s[58:59]
	s_nop 0
	v_readfirstlane_b32 s94, v220
	v_readfirstlane_b32 s95, v221
	v_readfirstlane_b32 s96, v222
	v_readfirstlane_b32 s97, v223
	s_nop 3
	s_sub_u32 s94, s94, 0x80
	s_subb_u32 s95, s95, 0
	s_add_u32 s98, s94, 0xc000
	s_addc_u32 s99, s95, 0
	s_add_u32 s100, s96, 0x6000
	s_addc_u32 s101, s97, 0
	v_subrev_u32_e32 v192, s94, v220
	v_subrev_u32_e32 v193, s96, v222
	s_cbranch_vccnz .LBB0_371
	s_mov_b32 m0, s70
	v_lshl_add_u64 v[2:3], v[220:221], 0, s[38:39]
	global_load_lds_dwordx4 v[220:221], off
	s_mov_b32 m0, s68
	s_nop 0
	global_load_lds_dwordx4 v[222:223], off
	s_mov_b32 m0, s72
	s_nop 0
	global_load_lds_dwordx4 v[2:3], off
	s_mov_b32 m0, s74
	v_lshl_add_u64 v[2:3], v[222:223], 0, s[40:41]
	global_load_lds_dwordx4 v[2:3], off
.LBB0_371:
	s_mov_b32 m0, s76
	v_lshl_add_u64 v[2:3], v[220:221], 0, s[42:43]
	global_load_lds_dwordx4 v[2:3], off
	s_mov_b32 m0, s78
	v_lshl_add_u64 v[2:3], v[222:223], 0, s[38:39]
	global_load_lds_dwordx4 v[2:3], off
	s_waitcnt vmcnt(2)
	s_waitcnt lgkmcnt(0)
	s_barrier
	ds_read_b128 v[22:25], v243 offset:32768
	ds_read_b128 v[18:21], v242 offset:32768
	ds_read_b128 v[34:37], v242 offset:36864
	ds_read_b128 v[38:41], v243 offset:36864
	v_mov_b64_e32 v[2:3], s[8:9]
	v_mov_b64_e32 v[4:5], s[10:11]
	v_mov_b64_e32 v[6:7], s[12:13]
	v_mov_b64_e32 v[8:9], s[14:15]
	v_mov_b64_e32 v[10:11], s[16:17]
	v_mov_b64_e32 v[12:13], s[18:19]
	v_mov_b64_e32 v[14:15], s[20:21]
	v_mov_b64_e32 v[16:17], s[22:23]
	s_nop 1
	s_waitcnt vmcnt(0) lgkmcnt(0)
	v_mfma_scale_f32_32x32x64_f8f6f4 v[18:33], v[18:25], v[176:183], v[2:17], v240, v239 op_sel_hi:[0,0,0]
	s_xor_b64 s[48:49], s[54:55], -1
	s_add_u32 s56, s56, s36
	s_addc_u32 s57, s57, 0
	v_lshl_add_u64 v[224:225], v[216:217], 0, s[58:59]
	v_lshl_add_u64 v[226:227], v[218:219], 0, s[56:57]
	s_mov_b32 s45, 0
	s_mov_b32 s47, 0
	v_mfma_scale_f32_32x32x64_f8f6f4 v[2:17], v[34:41], v[176:183], v[2:17], v240, v239 op_sel_hi:[0,0,0]
	ds_read_b128 v[38:41], v245 offset:32768
	ds_read_b128 v[34:37], v244 offset:32768
	ds_read_b128 v[42:45], v244 offset:36864
	ds_read_b128 v[46:49], v245 offset:36864
	s_waitcnt lgkmcnt(2)
	v_mfma_scale_f32_32x32x64_f8f6f4 v[18:33], v[34:41], v[184:191], v[18:33], v240, v239 op_sel_hi:[0,0,0]
	s_waitcnt lgkmcnt(0)
	v_mfma_scale_f32_32x32x64_f8f6f4 v[2:17], v[42:49], v[184:191], v[2:17], v240, v239 op_sel_hi:[0,0,0]
	s_nop 15
	s_nop 1
	v_max_f32_e32 v1, v19, v19
	v_max_f32_e32 v34, v18, v18
	v_max_f32_e32 v1, v34, v1
	v_max3_f32 v1, v1, v20, v21
	v_max3_f32 v1, v1, v22, v23
	v_max3_f32 v1, v1, v24, v25
	v_max3_f32 v1, v1, v26, v27
	v_max3_f32 v1, v1, v28, v29
	v_max3_f32 v1, v1, v30, v31
	v_max3_f32 v1, v1, v32, v33
	v_max3_f32 v1, v1, v2, v3
	v_max3_f32 v1, v1, v4, v5
	v_max3_f32 v1, v1, v6, v7
	v_max3_f32 v1, v1, v8, v9
	v_max3_f32 v1, v1, v10, v11
	v_max3_f32 v1, v1, v12, v13
	v_max3_f32 v1, v1, v14, v15
	v_max3_f32 v1, v1, v16, v17
	v_mov_b32_e32 v34, v1
	s_nop 1
	v_permlane32_swap_b32_e32 v1, v34
	v_max_f32_e32 v34, v34, v34
	v_max_f32_e32 v1, v1, v1
	v_max_f32_e32 v1, v1, v34
	v_add_f32_e32 v1, 0xc0a00000, v1
	v_sub_f32_e32 v18, v18, v1
	v_sub_f32_e32 v19, v19, v1
	v_sub_f32_e32 v20, v20, v1
	v_sub_f32_e32 v21, v21, v1
	v_sub_f32_e32 v22, v22, v1
	v_sub_f32_e32 v23, v23, v1
	v_sub_f32_e32 v24, v24, v1
	v_sub_f32_e32 v25, v25, v1
	v_sub_f32_e32 v26, v26, v1
	v_sub_f32_e32 v27, v27, v1
	v_sub_f32_e32 v28, v28, v1
	v_sub_f32_e32 v29, v29, v1
	v_sub_f32_e32 v30, v30, v1
	v_sub_f32_e32 v31, v31, v1
	v_sub_f32_e32 v32, v32, v1
	v_sub_f32_e32 v33, v33, v1
	v_exp_f32_e32 v144, v18
	v_exp_f32_e32 v145, v19
	v_exp_f32_e32 v146, v20
	v_exp_f32_e32 v147, v21
	v_exp_f32_e32 v148, v22
	v_exp_f32_e32 v149, v23
	v_exp_f32_e32 v150, v24
	v_exp_f32_e32 v151, v25
	v_exp_f32_e32 v152, v26
	v_exp_f32_e32 v153, v27
	v_exp_f32_e32 v154, v28
	v_exp_f32_e32 v155, v29
	v_exp_f32_e32 v156, v30
	v_exp_f32_e32 v157, v31
	v_exp_f32_e32 v158, v32
	v_exp_f32_e32 v159, v33
	v_sub_f32_e32 v125, v15, v1
	v_sub_f32_e32 v124, v14, v1
	v_mov_b32_e32 v14, v0
	v_mov_b32_e32 v15, v0
	v_sub_f32_e32 v96, 0x40a00000, v1
	v_sub_f32_e32 v127, v17, v1
	v_sub_f32_e32 v126, v16, v1
	v_sub_f32_e32 v123, v13, v1
	v_sub_f32_e32 v122, v12, v1
	v_sub_f32_e32 v121, v11, v1
	v_sub_f32_e32 v120, v10, v1
	v_sub_f32_e32 v119, v9, v1
	v_sub_f32_e32 v118, v8, v1
	v_sub_f32_e32 v117, v7, v1
	v_sub_f32_e32 v116, v6, v1
	v_sub_f32_e32 v115, v5, v1
	v_sub_f32_e32 v114, v4, v1
	v_sub_f32_e32 v113, v3, v1
	v_sub_f32_e32 v112, v2, v1
	v_mov_b32_e32 v1, v0
	v_mov_b32_e32 v2, v0
	v_mov_b32_e32 v3, v0
	v_mov_b32_e32 v4, v0
	v_mov_b32_e32 v5, v0
	v_mov_b32_e32 v6, v0
	v_mov_b32_e32 v7, v0
	v_mov_b32_e32 v8, v0
	v_mov_b32_e32 v9, v0
	v_mov_b32_e32 v10, v0
	v_mov_b32_e32 v11, v0
	v_mov_b32_e32 v12, v0
	v_mov_b32_e32 v13, v0
	v_mov_b64_e32 v[78:79], v[14:15]
	v_mov_b64_e32 v[62:63], v[14:15]
	v_mov_b64_e32 v[46:47], v[14:15]
	v_mov_b64_e32 v[30:31], v[14:15]
	v_mov_b64_e32 v[94:95], v[14:15]
	v_mov_b32_e32 v97, v96
	v_mov_b32_e32 v98, v96
	v_mov_b32_e32 v99, v96
	v_mov_b32_e32 v100, v96
	v_mov_b32_e32 v101, v96
	v_mov_b32_e32 v102, v96
	v_mov_b32_e32 v103, v96
	v_mov_b32_e32 v104, v96
	v_mov_b32_e32 v105, v96
	v_mov_b32_e32 v106, v96
	v_mov_b32_e32 v107, v96
	v_mov_b32_e32 v108, v96
	v_mov_b32_e32 v109, v96
	v_mov_b32_e32 v110, v96
	v_mov_b32_e32 v111, v96
	v_mov_b64_e32 v[76:77], v[12:13]
	v_mov_b64_e32 v[74:75], v[10:11]
	v_mov_b64_e32 v[72:73], v[8:9]
	v_mov_b64_e32 v[70:71], v[6:7]
	v_mov_b64_e32 v[68:69], v[4:5]
	v_mov_b64_e32 v[66:67], v[2:3]
	v_mov_b64_e32 v[64:65], v[0:1]
	v_mov_b64_e32 v[60:61], v[12:13]
	v_mov_b64_e32 v[58:59], v[10:11]
	v_mov_b64_e32 v[56:57], v[8:9]
	v_mov_b64_e32 v[54:55], v[6:7]
	v_mov_b64_e32 v[52:53], v[4:5]
	v_mov_b64_e32 v[50:51], v[2:3]
	v_mov_b64_e32 v[48:49], v[0:1]
	v_mov_b64_e32 v[44:45], v[12:13]
	v_mov_b64_e32 v[42:43], v[10:11]
	v_mov_b64_e32 v[40:41], v[8:9]
	v_mov_b64_e32 v[38:39], v[6:7]
	v_mov_b64_e32 v[36:37], v[4:5]
	v_mov_b64_e32 v[34:35], v[2:3]
	v_mov_b64_e32 v[32:33], v[0:1]
	v_mov_b64_e32 v[28:29], v[12:13]
	v_mov_b64_e32 v[26:27], v[10:11]
	v_mov_b64_e32 v[24:25], v[8:9]
	v_mov_b64_e32 v[22:23], v[6:7]
	v_mov_b64_e32 v[20:21], v[4:5]
	v_mov_b64_e32 v[18:19], v[2:3]
	v_mov_b64_e32 v[16:17], v[0:1]
	v_mov_b64_e32 v[92:93], v[12:13]
	v_mov_b64_e32 v[90:91], v[10:11]
	v_mov_b64_e32 v[88:89], v[8:9]
	v_mov_b64_e32 v[86:87], v[6:7]
	v_mov_b64_e32 v[84:85], v[4:5]
	v_mov_b64_e32 v[82:83], v[2:3]
	v_mov_b64_e32 v[80:81], v[0:1]
	s_cmp_lg_u32 s92, 0
	s_cbranch_scc1 .LgB_374
	s_branch .LBB0_374

; #define SBAR() __builtin_amdgcn_sched_barrier(0)
; #define DMA(slot, t) do { \
;     __builtin_amdgcn_global_load_lds((const unsigned*)(Kg + (long)(t) * (64 * 256)), (LAS unsigned*)(L3 + K_OFF + (slot) * SHM_T + wid * 1024), 16, 0, 0); \
;     __builtin_amdgcn_global_load_lds((const unsigned*)(Vg + (long)(t) * 8192), (LAS unsigned*)(L3 + (slot) * SHM_T + wid * 1024), 16, 0, 0); } while (0)
; #define QKT(P0, P1, b) qkt(P0, P1, nm, K_lds + (b) * SHM_T, qr, ko, c00, c01, c10, c11)
; #define PIPE1() do { SGB(0x100, 8); SGB(0x400, 4); SGB(0x008, 1); SGB(0x400, 4); SGB(0x008, 1); SGB(0x400, 4); SGB(0x008, 1); SGB(0x400, 4); SGB(0x008, 1); } while (0)
; #define HALF2(Y0, Y1, alY, b) do { PVL(b); const float pm_ = max32(Y0, Y1); adjustSM(Y0, Y1, nm, alY, pm_); SBAR(); \
;     PVM(); exp16(Y0); asm volatile("" : "+v"(Y0)); \
;     SGB(0x008, 1); SGB(0x400, 3); SGB(0x008, 1); SGB(0x400, 3); SGB(0x008, 1); SGB(0x400, 3); SGB(0x008, 1); SGB(0x400, 3); SGB(0x008, 1); SGB(0x400, 4); SBAR(); } while (0)
; __device__ __forceinline__ void body(const unsigned char* Q8b, const unsigned char* K8h, const unsigned char* VT8h, const bf16_t* Gb, bf16_t* Ob, int seq, char* lds, const int wid, ...
;     ...
;     SBAR(); QKT(pB0, pB1, (s0 + 1) & 3);
;     finishSM(pA0, pA1, pf); PIPE1(); SBAR();
;     DMA((s0 + 3) & 3, i + 3);
;     SBAR();
;     HALF2(pB0, pB1, alB, s0);
.LBB0_374:
	ds_read_b128 v[2:5], v242 offset:40960
	ds_read_b128 v[6:9], v243 offset:40960
	ds_read_b128 v[128:131], v242 offset:45056
	ds_read_b128 v[132:135], v243 offset:45056
	ds_read_b128 v[194:197], v244 offset:40960
	ds_read_b128 v[198:201], v245 offset:40960
	ds_read_b128 v[246:249], v244 offset:45056
	ds_read_b128 v[250:253], v245 offset:45056
	v_exp_f32_e32 v1, v112
	v_exp_f32_e32 v10, v113
	v_exp_f32_e32 v11, v114
	v_exp_f32_e32 v12, v115
	s_waitcnt lgkmcnt(6)
	s_setprio 1
	v_mfma_scale_f32_32x32x64_f8f6f4 v[160:175], v[2:9], v[176:183], v[96:111], v240, v239 op_sel_hi:[0,0,0]
	v_exp_f32_e32 v6, v116
	v_exp_f32_e32 v7, v117
	v_exp_f32_e32 v8, v118
	v_exp_f32_e32 v9, v119
	v_cvt_pk_fp8_f32 v5, v6, v7
	v_cvt_pk_fp8_f32 v3, v1, v10
	v_cvt_pk_fp8_f32 v5, v8, v9 op_sel:[0,0,1]
	s_waitcnt lgkmcnt(4)
	v_mfma_scale_f32_32x32x64_f8f6f4 v[128:143], v[128:135], v[176:183], v[96:111], v240, v239 op_sel_hi:[0,0,0]
	v_exp_f32_e32 v13, v120
	v_exp_f32_e32 v14, v121
	v_exp_f32_e32 v15, v122
	v_exp_f32_e32 v112, v123
	v_cvt_pk_fp8_f32 v2, v144, v145
	v_cvt_pk_fp8_f32 v4, v148, v149
	v_cvt_pk_fp8_f32 v6, v152, v153
	v_cvt_pk_fp8_f32 v7, v13, v14
	v_cvt_pk_fp8_f32 v8, v156, v157
	v_cvt_pk_fp8_f32 v2, v146, v147 op_sel:[0,0,1]
	v_cvt_pk_fp8_f32 v3, v11, v12 op_sel:[0,0,1]
	v_cvt_pk_fp8_f32 v4, v150, v151 op_sel:[0,0,1]
	v_cvt_pk_fp8_f32 v6, v154, v155 op_sel:[0,0,1]
	v_cvt_pk_fp8_f32 v7, v15, v112 op_sel:[0,0,1]
	v_cvt_pk_fp8_f32 v8, v158, v159 op_sel:[0,0,1]
	s_waitcnt lgkmcnt(2)
	v_mfma_scale_f32_32x32x64_f8f6f4 v[160:175], v[194:201], v[184:191], v[160:175], v240, v239 op_sel_hi:[0,0,0]
	v_exp_f32_e32 v113, v124
	v_exp_f32_e32 v114, v125
	v_exp_f32_e32 v1, v126
	v_exp_f32_e32 v10, v127
	v_cvt_pk_fp8_f32 v9, v113, v114
	s_waitcnt lgkmcnt(0)
	v_cvt_pk_fp8_f32 v9, v1, v10 op_sel:[0,0,1]
	v_mfma_scale_f32_32x32x64_f8f6f4 v[128:143], v[246:253], v[184:191], v[128:143], v240, v239 op_sel_hi:[0,0,0]
	s_setprio 0
	s_add_i32 m0, s68, 0xe000
	ds_read_b128 v[194:197], v254
	global_load_lds_dwordx4 v192, s[98:99]
	s_add_i32 m0, s68, 0x6000
	ds_read_b128 v[148:151], v254 offset:2048
	global_load_lds_dwordx4 v193, s[100:101]
	ds_read_b128 v[198:201], v255
	ds_read_b128 v[152:155], v255 offset:2048
	ds_read_b128 v[120:123], v254 offset:4096
	ds_read_b128 v[112:115], v254 offset:6144
	ds_read_b128 v[124:127], v255 offset:4096
	ds_read_b128 v[116:119], v255 offset:6144
	v_max_f32_e32 v1, v160, v161
	v_max3_f32 v1, v1, v162, v163
	v_max3_f32 v1, v1, v164, v165
	v_max3_f32 v1, v1, v166, v167
	v_max3_f32 v1, v1, v168, v169
	v_max3_f32 v1, v1, v170, v171
	v_max3_f32 v1, v1, v172, v173
	v_max3_f32 v1, v1, v174, v175
	v_max3_f32 v1, v1, v128, v129
	v_max3_f32 v1, v1, v130, v131
	v_max3_f32 v1, v1, v132, v133
	v_max3_f32 v1, v1, v134, v135
	v_max3_f32 v1, v1, v136, v137
	v_max3_f32 v1, v1, v138, v139
	v_max3_f32 v1, v1, v140, v141
	v_max3_f32 v1, v1, v142, v143
	v_cmp_lt_f32_e32 vcc, s80, v1
	s_cbranch_vccnz .LBB0_383

; #define SBAR() __builtin_amdgcn_sched_barrier(0)
; #define DMA(slot, t) do { \
;     __builtin_amdgcn_global_load_lds((const unsigned*)(Kg + (long)(t) * (64 * 256)), (LAS unsigned*)(L3 + K_OFF + (slot) * SHM_T + wid * 1024), 16, 0, 0); \
;     __builtin_amdgcn_global_load_lds((const unsigned*)(Vg + (long)(t) * 8192), (LAS unsigned*)(L3 + (slot) * SHM_T + wid * 1024), 16, 0, 0); } while (0)
; #define QKT(P0, P1, b) qkt(P0, P1, nm, K_lds + (b) * SHM_T, qr, ko, c00, c01, c10, c11)
; #define PIPE1() do { SGB(0x100, 8); SGB(0x400, 4); SGB(0x008, 1); SGB(0x400, 4); SGB(0x008, 1); SGB(0x400, 4); SGB(0x008, 1); SGB(0x400, 4); SGB(0x008, 1); } while (0)
; #define HALF2(Y0, Y1, alY, b) do { PVL(b); const float pm_ = max32(Y0, Y1); adjustSM(Y0, Y1, nm, alY, pm_); SBAR(); \
;     PVM(); exp16(Y0); asm volatile("" : "+v"(Y0)); \
;     SGB(0x008, 1); SGB(0x400, 3); SGB(0x008, 1); SGB(0x400, 3); SGB(0x008, 1); SGB(0x400, 3); SGB(0x008, 1); SGB(0x400, 3); SGB(0x008, 1); SGB(0x400, 4); SBAR(); } while (0)
; __device__ __forceinline__ void body(const unsigned char* Q8b, const unsigned char* K8h, const unsigned char* VT8h, const bf16_t* Gb, bf16_t* Ob, int seq, char* lds, const int wid, ...
;     ...
;     SBAR(); QKT(pA0, pA1, (s0 + 2) & 3);
;     finishSM(pB0, pB1, pf); PIPE1(); SBAR();
;     { const int t4 = (i + 4 < NT) ? i + 4 : NT - 1; DMA(s0, t4); }
;     SBAR();
;     HALF2(pA0, pA1, alA, (s0 + 1) & 3);
.LBB0_379:
	s_waitcnt lgkmcnt(0)
	s_barrier
	ds_read_b128 v[2:5], v242 offset:49152
	ds_read_b128 v[6:9], v243 offset:49152
	ds_read_b128 v[112:115], v242 offset:53248
	ds_read_b128 v[116:119], v243 offset:53248
	ds_read_b128 v[194:197], v244 offset:49152
	ds_read_b128 v[198:201], v245 offset:49152
	ds_read_b128 v[246:249], v244 offset:53248
	ds_read_b128 v[250:253], v245 offset:53248
	v_exp_f32_e32 v1, v128
	v_exp_f32_e32 v10, v129
	v_exp_f32_e32 v11, v130
	v_exp_f32_e32 v12, v131
	s_waitcnt lgkmcnt(6)
	s_setprio 1
	v_mfma_scale_f32_32x32x64_f8f6f4 v[160:175], v[2:9], v[176:183], v[96:111], v240, v239 op_sel_hi:[0,0,0]
	v_exp_f32_e32 v6, v132
	v_exp_f32_e32 v7, v133
	v_exp_f32_e32 v8, v134
	v_exp_f32_e32 v9, v135
	v_cvt_pk_fp8_f32 v5, v6, v7
	v_cvt_pk_fp8_f32 v2, v144, v145
	v_cvt_pk_fp8_f32 v5, v8, v9 op_sel:[0,0,1]
	s_waitcnt lgkmcnt(4)
	v_mfma_scale_f32_32x32x64_f8f6f4 v[112:127], v[112:119], v[176:183], v[96:111], v240, v239 op_sel_hi:[0,0,0]
	v_exp_f32_e32 v13, v136
	v_exp_f32_e32 v14, v137
	v_exp_f32_e32 v15, v138
	v_exp_f32_e32 v128, v139
	v_cvt_pk_fp8_f32 v3, v1, v10
	v_cvt_pk_fp8_f32 v4, v148, v149
	v_cvt_pk_fp8_f32 v6, v152, v153
	v_cvt_pk_fp8_f32 v7, v13, v14
	v_cvt_pk_fp8_f32 v8, v156, v157
	v_cvt_pk_fp8_f32 v2, v146, v147 op_sel:[0,0,1]
	v_cvt_pk_fp8_f32 v3, v11, v12 op_sel:[0,0,1]
	v_cvt_pk_fp8_f32 v4, v150, v151 op_sel:[0,0,1]
	v_cvt_pk_fp8_f32 v6, v154, v155 op_sel:[0,0,1]
	v_cvt_pk_fp8_f32 v7, v15, v128 op_sel:[0,0,1]
	v_cvt_pk_fp8_f32 v8, v158, v159 op_sel:[0,0,1]
	s_waitcnt lgkmcnt(2)
	v_mfma_scale_f32_32x32x64_f8f6f4 v[160:175], v[194:201], v[184:191], v[160:175], v240, v239 op_sel_hi:[0,0,0]
	v_exp_f32_e32 v129, v140
	v_exp_f32_e32 v130, v141
	v_exp_f32_e32 v131, v142
	v_exp_f32_e32 v132, v143
	v_cvt_pk_fp8_f32 v9, v129, v130
	s_waitcnt lgkmcnt(0)
	v_cvt_pk_fp8_f32 v9, v131, v132 op_sel:[0,0,1]
	v_mfma_scale_f32_32x32x64_f8f6f4 v[112:127], v[246:253], v[184:191], v[112:127], v240, v239 op_sel_hi:[0,0,0]
	s_setprio 0
	s_min_u32 s36, s45, 0x7b
	s_add_i32 s56, s36, 4
	s_lshl_b32 s36, s56, 14
	s_add_i32 s57, s68, 0x0
	s_add_u32 s88, s94, s36
	s_addc_u32 s89, s95, 0
	s_add_i32 m0, s57, 0x8000
	s_lshl_b32 s36, s56, 13
	s_add_u32 s90, s96, s36
	s_addc_u32 s91, s97, 0
	global_load_lds_dwordx4 v192, s[88:89]
	s_mov_b32 m0, s57
	ds_read_b128 v[194:197], v254 offset:8192
	global_load_lds_dwordx4 v193, s[90:91]
	ds_read_b128 v[148:151], v254 offset:10240
	ds_read_b128 v[198:201], v255 offset:8192
	ds_read_b128 v[152:155], v255 offset:10240
	ds_read_b128 v[136:139], v254 offset:12288
	ds_read_b128 v[128:131], v254 offset:14336
	ds_read_b128 v[140:143], v255 offset:12288
	ds_read_b128 v[132:135], v255 offset:14336
	v_max_f32_e32 v1, v160, v161
	v_max3_f32 v1, v1, v162, v163
	v_max3_f32 v1, v1, v164, v165
	v_max3_f32 v1, v1, v166, v167
	v_max3_f32 v1, v1, v168, v169
	v_max3_f32 v1, v1, v170, v171
	v_max3_f32 v1, v1, v172, v173
	v_max3_f32 v1, v1, v174, v175
	v_max3_f32 v1, v1, v112, v113
	v_max3_f32 v1, v1, v114, v115
	v_max3_f32 v1, v1, v116, v117
	v_max3_f32 v1, v1, v118, v119
	v_max3_f32 v1, v1, v120, v121
	v_max3_f32 v1, v1, v122, v123
	v_max3_f32 v1, v1, v124, v125
	v_max3_f32 v1, v1, v126, v127
	v_cmp_lt_f32_e32 vcc, s80, v1
	s_cbranch_vccnz .LBB0_384

; #define SBAR() __builtin_amdgcn_sched_barrier(0)
; #define DMA(slot, t) do { \
;     __builtin_amdgcn_global_load_lds((const unsigned*)(Kg + (long)(t) * (64 * 256)), (LAS unsigned*)(L3 + K_OFF + (slot) * SHM_T + wid * 1024), 16, 0, 0); \
;     __builtin_amdgcn_global_load_lds((const unsigned*)(Vg + (long)(t) * 8192), (LAS unsigned*)(L3 + (slot) * SHM_T + wid * 1024), 16, 0, 0); } while (0)
; #define QKT(P0, P1, b) qkt(P0, P1, nm, K_lds + (b) * SHM_T, qr, ko, c00, c01, c10, c11)
; #define PIPE1() do { SGB(0x100, 8); SGB(0x400, 4); SGB(0x008, 1); SGB(0x400, 4); SGB(0x008, 1); SGB(0x400, 4); SGB(0x008, 1); SGB(0x400, 4); SGB(0x008, 1); } while (0)
; #define HALF2(Y0, Y1, alY, b) do { PVL(b); const float pm_ = max32(Y0, Y1); adjustSM(Y0, Y1, nm, alY, pm_); SBAR(); \
;     PVM(); exp16(Y0); asm volatile("" : "+v"(Y0)); \
;     SGB(0x008, 1); SGB(0x400, 3); SGB(0x008, 1); SGB(0x400, 3); SGB(0x008, 1); SGB(0x400, 3); SGB(0x008, 1); SGB(0x400, 3); SGB(0x008, 1); SGB(0x400, 4); SBAR(); } while (0)
; __device__ __forceinline__ void body(const unsigned char* Q8b, const unsigned char* K8h, const unsigned char* VT8h, const bf16_t* Gb, bf16_t* Ob, int seq, char* lds, const int wid, ...
;     ...
;     SBAR(); QKT(pB0, pB1, (s0 + 1) & 3);
;     finishSM(pA0, pA1, pf); PIPE1(); SBAR();
;     DMA((s0 + 3) & 3, i + 3);
;     SBAR();
;     HALF2(pB0, pB1, alB, s0);
.Lc2_374:
	ds_read_b128 v[2:5], v242 offset:57344
	ds_read_b128 v[6:9], v243 offset:57344
	ds_read_b128 v[128:131], v242 offset:61440
	ds_read_b128 v[132:135], v243 offset:61440
	ds_read_b128 v[194:197], v244 offset:57344
	ds_read_b128 v[198:201], v245 offset:57344
	ds_read_b128 v[246:249], v244 offset:61440
	ds_read_b128 v[250:253], v245 offset:61440
	v_exp_f32_e32 v1, v112
	v_exp_f32_e32 v10, v113
	v_exp_f32_e32 v11, v114
	v_exp_f32_e32 v12, v115
	s_waitcnt lgkmcnt(6)
	s_setprio 1
	v_mfma_scale_f32_32x32x64_f8f6f4 v[160:175], v[2:9], v[176:183], v[96:111], v240, v239 op_sel_hi:[0,0,0]
	v_exp_f32_e32 v6, v116
	v_exp_f32_e32 v7, v117
	v_exp_f32_e32 v8, v118
	v_exp_f32_e32 v9, v119
	v_cvt_pk_fp8_f32 v5, v6, v7
	v_cvt_pk_fp8_f32 v3, v1, v10
	v_cvt_pk_fp8_f32 v5, v8, v9 op_sel:[0,0,1]
	s_waitcnt lgkmcnt(4)
	v_mfma_scale_f32_32x32x64_f8f6f4 v[128:143], v[128:135], v[176:183], v[96:111], v240, v239 op_sel_hi:[0,0,0]
	v_exp_f32_e32 v13, v120
	v_exp_f32_e32 v14, v121
	v_exp_f32_e32 v15, v122
	v_exp_f32_e32 v112, v123
	v_cvt_pk_fp8_f32 v2, v144, v145
	v_cvt_pk_fp8_f32 v4, v148, v149
	v_cvt_pk_fp8_f32 v6, v152, v153
	v_cvt_pk_fp8_f32 v7, v13, v14
	v_cvt_pk_fp8_f32 v8, v156, v157
	v_cvt_pk_fp8_f32 v2, v146, v147 op_sel:[0,0,1]
	v_cvt_pk_fp8_f32 v3, v11, v12 op_sel:[0,0,1]
	v_cvt_pk_fp8_f32 v4, v150, v151 op_sel:[0,0,1]
	v_cvt_pk_fp8_f32 v6, v154, v155 op_sel:[0,0,1]
	v_cvt_pk_fp8_f32 v7, v15, v112 op_sel:[0,0,1]
	v_cvt_pk_fp8_f32 v8, v158, v159 op_sel:[0,0,1]
	s_waitcnt lgkmcnt(2)
	v_mfma_scale_f32_32x32x64_f8f6f4 v[160:175], v[194:201], v[184:191], v[160:175], v240, v239 op_sel_hi:[0,0,0]
	v_exp_f32_e32 v113, v124
	v_exp_f32_e32 v114, v125
	v_exp_f32_e32 v1, v126
	v_exp_f32_e32 v10, v127
	v_cvt_pk_fp8_f32 v9, v113, v114
	s_waitcnt lgkmcnt(0)
	v_cvt_pk_fp8_f32 v9, v1, v10 op_sel:[0,0,1]
	v_mfma_scale_f32_32x32x64_f8f6f4 v[128:143], v[246:253], v[184:191], v[128:143], v240, v239 op_sel_hi:[0,0,0]
	s_setprio 0
	s_add_i32 m0, s68, 0xa000
	ds_read_b128 v[194:197], v254 offset:16384
	global_load_lds_dwordx4 v192, s[98:99]
	s_add_i32 m0, s68, 0x2000
	ds_read_b128 v[148:151], v254 offset:18432
	global_load_lds_dwordx4 v193, s[100:101]
	ds_read_b128 v[198:201], v255 offset:16384
	ds_read_b128 v[152:155], v255 offset:18432
	ds_read_b128 v[120:123], v254 offset:20480
	ds_read_b128 v[112:115], v254 offset:22528
	ds_read_b128 v[124:127], v255 offset:20480
	ds_read_b128 v[116:119], v255 offset:22528
	v_max_f32_e32 v1, v160, v161
	v_max3_f32 v1, v1, v162, v163
	v_max3_f32 v1, v1, v164, v165
	v_max3_f32 v1, v1, v166, v167
	v_max3_f32 v1, v1, v168, v169
	v_max3_f32 v1, v1, v170, v171
	v_max3_f32 v1, v1, v172, v173
	v_max3_f32 v1, v1, v174, v175
	v_max3_f32 v1, v1, v128, v129
	v_max3_f32 v1, v1, v130, v131
	v_max3_f32 v1, v1, v132, v133
	v_max3_f32 v1, v1, v134, v135
	v_max3_f32 v1, v1, v136, v137
	v_max3_f32 v1, v1, v138, v139
	v_max3_f32 v1, v1, v140, v141
	v_max3_f32 v1, v1, v142, v143
	v_cmp_lt_f32_e32 vcc, s80, v1
	s_cbranch_vccnz .Lc2_383

; #define SBAR() __builtin_amdgcn_sched_barrier(0)
; #define DMA(slot, t) do { \
;     __builtin_amdgcn_global_load_lds((const unsigned*)(Kg + (long)(t) * (64 * 256)), (LAS unsigned*)(L3 + K_OFF + (slot) * SHM_T + wid * 1024), 16, 0, 0); \
;     __builtin_amdgcn_global_load_lds((const unsigned*)(Vg + (long)(t) * 8192), (LAS unsigned*)(L3 + (slot) * SHM_T + wid * 1024), 16, 0, 0); } while (0)
; #define QKT(P0, P1, b) qkt(P0, P1, nm, K_lds + (b) * SHM_T, qr, ko, c00, c01, c10, c11)
; #define PIPE1() do { SGB(0x100, 8); SGB(0x400, 4); SGB(0x008, 1); SGB(0x400, 4); SGB(0x008, 1); SGB(0x400, 4); SGB(0x008, 1); SGB(0x400, 4); SGB(0x008, 1); } while (0)
; #define HALF2(Y0, Y1, alY, b) do { PVL(b); const float pm_ = max32(Y0, Y1); adjustSM(Y0, Y1, nm, alY, pm_); SBAR(); \
;     PVM(); exp16(Y0); asm volatile("" : "+v"(Y0)); \
;     SGB(0x008, 1); SGB(0x400, 3); SGB(0x008, 1); SGB(0x400, 3); SGB(0x008, 1); SGB(0x400, 3); SGB(0x008, 1); SGB(0x400, 3); SGB(0x008, 1); SGB(0x400, 4); SBAR(); } while (0)
; __device__ __forceinline__ void body(const unsigned char* Q8b, const unsigned char* K8h, const unsigned char* VT8h, const bf16_t* Gb, bf16_t* Ob, int seq, char* lds, const int wid, ...
;     ...
;     SBAR(); QKT(pA0, pA1, (s0 + 2) & 3);
;     finishSM(pB0, pB1, pf); PIPE1(); SBAR();
;     { const int t4 = (i + 4 < NT) ? i + 4 : NT - 1; DMA(s0, t4); }
;     SBAR();
;     HALF2(pA0, pA1, alA, (s0 + 1) & 3);
.Lc2_379:
	s_waitcnt lgkmcnt(0)
	s_barrier
	ds_read_b128 v[2:5], v242 offset:32768
	ds_read_b128 v[6:9], v243 offset:32768
	ds_read_b128 v[112:115], v242 offset:36864
	ds_read_b128 v[116:119], v243 offset:36864
	ds_read_b128 v[194:197], v244 offset:32768
	ds_read_b128 v[198:201], v245 offset:32768
	ds_read_b128 v[246:249], v244 offset:36864
	ds_read_b128 v[250:253], v245 offset:36864
	v_exp_f32_e32 v1, v128
	v_exp_f32_e32 v10, v129
	v_exp_f32_e32 v11, v130
	v_exp_f32_e32 v12, v131
	s_waitcnt lgkmcnt(6)
	s_setprio 1
	v_mfma_scale_f32_32x32x64_f8f6f4 v[160:175], v[2:9], v[176:183], v[96:111], v240, v239 op_sel_hi:[0,0,0]
	v_exp_f32_e32 v6, v132
	v_exp_f32_e32 v7, v133
	v_exp_f32_e32 v8, v134
	v_exp_f32_e32 v9, v135
	v_cvt_pk_fp8_f32 v5, v6, v7
	v_cvt_pk_fp8_f32 v2, v144, v145
	v_cvt_pk_fp8_f32 v5, v8, v9 op_sel:[0,0,1]
	s_waitcnt lgkmcnt(4)
	v_mfma_scale_f32_32x32x64_f8f6f4 v[112:127], v[112:119], v[176:183], v[96:111], v240, v239 op_sel_hi:[0,0,0]
	v_exp_f32_e32 v13, v136
	v_exp_f32_e32 v14, v137
	v_exp_f32_e32 v15, v138
	v_exp_f32_e32 v128, v139
	v_cvt_pk_fp8_f32 v3, v1, v10
	v_cvt_pk_fp8_f32 v4, v148, v149
	v_cvt_pk_fp8_f32 v6, v152, v153
	v_cvt_pk_fp8_f32 v7, v13, v14
	v_cvt_pk_fp8_f32 v8, v156, v157
	v_cvt_pk_fp8_f32 v2, v146, v147 op_sel:[0,0,1]
	v_cvt_pk_fp8_f32 v3, v11, v12 op_sel:[0,0,1]
	v_cvt_pk_fp8_f32 v4, v150, v151 op_sel:[0,0,1]
	v_cvt_pk_fp8_f32 v6, v154, v155 op_sel:[0,0,1]
	v_cvt_pk_fp8_f32 v7, v15, v128 op_sel:[0,0,1]
	v_cvt_pk_fp8_f32 v8, v158, v159 op_sel:[0,0,1]
	s_waitcnt lgkmcnt(2)
	v_mfma_scale_f32_32x32x64_f8f6f4 v[160:175], v[194:201], v[184:191], v[160:175], v240, v239 op_sel_hi:[0,0,0]
	v_exp_f32_e32 v129, v140
	v_exp_f32_e32 v130, v141
	v_exp_f32_e32 v131, v142
	v_exp_f32_e32 v132, v143
	v_cvt_pk_fp8_f32 v9, v129, v130
	s_waitcnt lgkmcnt(0)
	v_cvt_pk_fp8_f32 v9, v131, v132 op_sel:[0,0,1]
	v_mfma_scale_f32_32x32x64_f8f6f4 v[112:127], v[246:253], v[184:191], v[112:127], v240, v239 op_sel_hi:[0,0,0]
	s_setprio 0
	s_min_u32 s36, s45, 0x7b
	s_add_i32 s56, s36, 4
	s_lshl_b32 s36, s56, 14
	s_add_i32 s57, s68, 0x4000
	s_add_u32 s88, s94, s36
	s_addc_u32 s89, s95, 0
	s_add_i32 m0, s57, 0x8000
	s_lshl_b32 s36, s56, 13
	s_add_u32 s90, s96, s36
	s_addc_u32 s91, s97, 0
	global_load_lds_dwordx4 v192, s[88:89]
	s_mov_b32 m0, s57
	ds_read_b128 v[194:197], v254 offset:24576
	global_load_lds_dwordx4 v193, s[90:91]
	ds_read_b128 v[148:151], v254 offset:26624
	ds_read_b128 v[198:201], v255 offset:24576
	ds_read_b128 v[152:155], v255 offset:26624
	ds_read_b128 v[136:139], v254 offset:28672
	ds_read_b128 v[128:131], v254 offset:30720
	ds_read_b128 v[140:143], v255 offset:28672
	ds_read_b128 v[132:135], v255 offset:30720
	v_max_f32_e32 v1, v160, v161
	v_max3_f32 v1, v1, v162, v163
	v_max3_f32 v1, v1, v164, v165
	v_max3_f32 v1, v1, v166, v167
	v_max3_f32 v1, v1, v168, v169
	v_max3_f32 v1, v1, v170, v171
	v_max3_f32 v1, v1, v172, v173
	v_max3_f32 v1, v1, v174, v175
	v_max3_f32 v1, v1, v112, v113
	v_max3_f32 v1, v1, v114, v115
	v_max3_f32 v1, v1, v116, v117
	v_max3_f32 v1, v1, v118, v119
	v_max3_f32 v1, v1, v120, v121
	v_max3_f32 v1, v1, v122, v123
	v_max3_f32 v1, v1, v124, v125
	v_max3_f32 v1, v1, v126, v127
	v_cmp_lt_f32_e32 vcc, s80, v1
	s_cbranch_vccnz .Lc2_384

; #define SBAR() __builtin_amdgcn_sched_barrier(0)
; #define DMA(slot, t) do { \
;     __builtin_amdgcn_global_load_lds((const unsigned*)(Kg + (long)(t) * (64 * 256)), (LAS unsigned*)(L3 + K_OFF + (slot) * SHM_T + wid * 1024), 16, 0, 0); \
;     __builtin_amdgcn_global_load_lds((const unsigned*)(Vg + (long)(t) * 8192), (LAS unsigned*)(L3 + (slot) * SHM_T + wid * 1024), 16, 0, 0); } while (0)
; #define QKT(P0, P1, b) qkt(P0, P1, nm, K_lds + (b) * SHM_T, qr, ko, c00, c01, c10, c11)
; #define PIPE1() do { SGB(0x100, 8); SGB(0x400, 4); SGB(0x008, 1); SGB(0x400, 4); SGB(0x008, 1); SGB(0x400, 4); SGB(0x008, 1); SGB(0x400, 4); SGB(0x008, 1); } while (0)
; #define HALF2(Y0, Y1, alY, b) do { PVL(b); const float pm_ = max32(Y0, Y1); adjustSM(Y0, Y1, nm, alY, pm_); SBAR(); \
;     PVM(); exp16(Y0); asm volatile("" : "+v"(Y0)); \
;     SGB(0x008, 1); SGB(0x400, 3); SGB(0x008, 1); SGB(0x400, 3); SGB(0x008, 1); SGB(0x400, 3); SGB(0x008, 1); SGB(0x400, 3); SGB(0x008, 1); SGB(0x400, 4); SBAR(); } while (0)
; __device__ __forceinline__ void body(const unsigned char* Q8b, const unsigned char* K8h, const unsigned char* VT8h, const bf16_t* Gb, bf16_t* Ob, int seq, char* lds, const int wid, ...
;     ...
;     SBAR(); QKT(pA0, pA1, (s0 + 2) & 3);
;     finishSM(pB0, pB1, pf); PIPE1(); SBAR();
;     { const int t4 = (i + 4 < NT) ? i + 4 : NT - 1; DMA(s0, t4); }
;     SBAR();
;     HALF2(pA0, pA1, alA, (s0 + 1) & 3);
.LgB_379:
	ds_read_b128 v[2:5], v242 offset:49152
	ds_read_b128 v[6:9], v243 offset:49152
	ds_read_b128 v[112:115], v242 offset:53248
	ds_read_b128 v[116:119], v243 offset:53248
	ds_read_b128 v[194:197], v244 offset:49152
	ds_read_b128 v[198:201], v245 offset:49152
	ds_read_b128 v[246:249], v244 offset:53248
	ds_read_b128 v[250:253], v245 offset:53248
	v_exp_f32_e32 v1, v128
	v_exp_f32_e32 v10, v129
	v_exp_f32_e32 v11, v130
	v_exp_f32_e32 v12, v131
	s_waitcnt lgkmcnt(6)
	s_setprio 1
	v_mfma_scale_f32_32x32x64_f8f6f4 v[160:175], v[2:9], v[176:183], v[96:111], v240, v239 op_sel_hi:[0,0,0]
	v_exp_f32_e32 v6, v132
	v_exp_f32_e32 v7, v133
	v_exp_f32_e32 v8, v134
	v_exp_f32_e32 v9, v135
	v_cvt_pk_fp8_f32 v5, v6, v7
	v_cvt_pk_fp8_f32 v2, v144, v145
	v_cvt_pk_fp8_f32 v5, v8, v9 op_sel:[0,0,1]
	s_waitcnt lgkmcnt(4)
	v_mfma_scale_f32_32x32x64_f8f6f4 v[112:127], v[112:119], v[176:183], v[96:111], v240, v239 op_sel_hi:[0,0,0]
	v_exp_f32_e32 v13, v136
	v_exp_f32_e32 v14, v137
	v_exp_f32_e32 v15, v138
	v_exp_f32_e32 v128, v139
	v_cvt_pk_fp8_f32 v3, v1, v10
	v_cvt_pk_fp8_f32 v4, v148, v149
	v_cvt_pk_fp8_f32 v6, v152, v153
	v_cvt_pk_fp8_f32 v7, v13, v14
	v_cvt_pk_fp8_f32 v8, v156, v157
	v_cvt_pk_fp8_f32 v2, v146, v147 op_sel:[0,0,1]
	v_cvt_pk_fp8_f32 v3, v11, v12 op_sel:[0,0,1]
	v_cvt_pk_fp8_f32 v4, v150, v151 op_sel:[0,0,1]
	v_cvt_pk_fp8_f32 v6, v154, v155 op_sel:[0,0,1]
	v_cvt_pk_fp8_f32 v7, v15, v128 op_sel:[0,0,1]
	v_cvt_pk_fp8_f32 v8, v158, v159 op_sel:[0,0,1]
	s_waitcnt lgkmcnt(2)
	v_mfma_scale_f32_32x32x64_f8f6f4 v[160:175], v[194:201], v[184:191], v[160:175], v240, v239 op_sel_hi:[0,0,0]
	v_exp_f32_e32 v129, v140
	v_exp_f32_e32 v130, v141
	v_exp_f32_e32 v131, v142
	v_exp_f32_e32 v132, v143
	v_cvt_pk_fp8_f32 v9, v129, v130
	s_waitcnt lgkmcnt(0)
	v_cvt_pk_fp8_f32 v9, v131, v132 op_sel:[0,0,1]
	v_mfma_scale_f32_32x32x64_f8f6f4 v[112:127], v[246:253], v[184:191], v[112:127], v240, v239 op_sel_hi:[0,0,0]
	s_setprio 0
	s_min_u32 s36, s45, 0x7b
	s_add_i32 s56, s36, 4
	s_lshl_b32 s36, s56, 14
	s_add_i32 s57, s68, 0x0
	s_add_u32 s88, s94, s36
	s_addc_u32 s89, s95, 0
	s_add_i32 m0, s57, 0x8000
	s_lshl_b32 s36, s56, 13
	s_add_u32 s90, s96, s36
	s_addc_u32 s91, s97, 0
	global_load_lds_dwordx4 v192, s[88:89]
	s_mov_b32 m0, s57
	ds_read_b128 v[194:197], v254 offset:8192
	global_load_lds_dwordx4 v193, s[90:91]
	ds_read_b128 v[148:151], v254 offset:10240
	ds_read_b128 v[198:201], v255 offset:8192
	ds_read_b128 v[152:155], v255 offset:10240
	ds_read_b128 v[136:139], v254 offset:12288
	ds_read_b128 v[128:131], v254 offset:14336
	ds_read_b128 v[140:143], v255 offset:12288
	ds_read_b128 v[132:135], v255 offset:14336
	v_max_f32_e32 v1, v160, v161
	v_max3_f32 v1, v1, v162, v163
	v_max3_f32 v1, v1, v164, v165
	v_max3_f32 v1, v1, v166, v167
	v_max3_f32 v1, v1, v168, v169
	v_max3_f32 v1, v1, v170, v171
	v_max3_f32 v1, v1, v172, v173
	v_max3_f32 v1, v1, v174, v175
	v_max3_f32 v1, v1, v112, v113
	v_max3_f32 v1, v1, v114, v115
	v_max3_f32 v1, v1, v116, v117
	v_max3_f32 v1, v1, v118, v119
	v_max3_f32 v1, v1, v120, v121
	v_max3_f32 v1, v1, v122, v123
	v_max3_f32 v1, v1, v124, v125
	v_max3_f32 v1, v1, v126, v127
	v_cmp_lt_f32_e32 vcc, s80, v1
	s_cbranch_vccnz .LgB_384

; #define SBAR() __builtin_amdgcn_sched_barrier(0)
; #define DMA(slot, t) do { \
;     __builtin_amdgcn_global_load_lds((const unsigned*)(Kg + (long)(t) * (64 * 256)), (LAS unsigned*)(L3 + K_OFF + (slot) * SHM_T + wid * 1024), 16, 0, 0); \
;     __builtin_amdgcn_global_load_lds((const unsigned*)(Vg + (long)(t) * 8192), (LAS unsigned*)(L3 + (slot) * SHM_T + wid * 1024), 16, 0, 0); } while (0)
; #define QKT(P0, P1, b) qkt(P0, P1, nm, K_lds + (b) * SHM_T, qr, ko, c00, c01, c10, c11)
; #define PIPE1() do { SGB(0x100, 8); SGB(0x400, 4); SGB(0x008, 1); SGB(0x400, 4); SGB(0x008, 1); SGB(0x400, 4); SGB(0x008, 1); SGB(0x400, 4); SGB(0x008, 1); } while (0)
; #define HALF2(Y0, Y1, alY, b) do { PVL(b); const float pm_ = max32(Y0, Y1); adjustSM(Y0, Y1, nm, alY, pm_); SBAR(); \
;     PVM(); exp16(Y0); asm volatile("" : "+v"(Y0)); \
;     SGB(0x008, 1); SGB(0x400, 3); SGB(0x008, 1); SGB(0x400, 3); SGB(0x008, 1); SGB(0x400, 3); SGB(0x008, 1); SGB(0x400, 3); SGB(0x008, 1); SGB(0x400, 4); SBAR(); } while (0)
; __device__ __forceinline__ void body(const unsigned char* Q8b, const unsigned char* K8h, const unsigned char* VT8h, const bf16_t* Gb, bf16_t* Ob, int seq, char* lds, const int wid, ...
;     ...
;     SBAR(); QKT(pA0, pA1, (s0 + 2) & 3);
;     finishSM(pB0, pB1, pf); PIPE1(); SBAR();
;     { const int t4 = (i + 4 < NT) ? i + 4 : NT - 1; DMA(s0, t4); }
;     SBAR();
;     HALF2(pA0, pA1, alA, (s0 + 1) & 3);
.LgBc2_379:
	ds_read_b128 v[2:5], v242 offset:32768
	ds_read_b128 v[6:9], v243 offset:32768
	ds_read_b128 v[112:115], v242 offset:36864
	ds_read_b128 v[116:119], v243 offset:36864
	ds_read_b128 v[194:197], v244 offset:32768
	ds_read_b128 v[198:201], v245 offset:32768
	ds_read_b128 v[246:249], v244 offset:36864
	ds_read_b128 v[250:253], v245 offset:36864
	v_exp_f32_e32 v1, v128
	v_exp_f32_e32 v10, v129
	v_exp_f32_e32 v11, v130
	v_exp_f32_e32 v12, v131
	s_waitcnt lgkmcnt(6)
	s_setprio 1
	v_mfma_scale_f32_32x32x64_f8f6f4 v[160:175], v[2:9], v[176:183], v[96:111], v240, v239 op_sel_hi:[0,0,0]
	v_exp_f32_e32 v6, v132
	v_exp_f32_e32 v7, v133
	v_exp_f32_e32 v8, v134
	v_exp_f32_e32 v9, v135
	v_cvt_pk_fp8_f32 v5, v6, v7
	v_cvt_pk_fp8_f32 v2, v144, v145
	v_cvt_pk_fp8_f32 v5, v8, v9 op_sel:[0,0,1]
	s_waitcnt lgkmcnt(4)
	v_mfma_scale_f32_32x32x64_f8f6f4 v[112:127], v[112:119], v[176:183], v[96:111], v240, v239 op_sel_hi:[0,0,0]
	v_exp_f32_e32 v13, v136
	v_exp_f32_e32 v14, v137
	v_exp_f32_e32 v15, v138
	v_exp_f32_e32 v128, v139
	v_cvt_pk_fp8_f32 v3, v1, v10
	v_cvt_pk_fp8_f32 v4, v148, v149
	v_cvt_pk_fp8_f32 v6, v152, v153
	v_cvt_pk_fp8_f32 v7, v13, v14
	v_cvt_pk_fp8_f32 v8, v156, v157
	v_cvt_pk_fp8_f32 v2, v146, v147 op_sel:[0,0,1]
	v_cvt_pk_fp8_f32 v3, v11, v12 op_sel:[0,0,1]
	v_cvt_pk_fp8_f32 v4, v150, v151 op_sel:[0,0,1]
	v_cvt_pk_fp8_f32 v6, v154, v155 op_sel:[0,0,1]
	v_cvt_pk_fp8_f32 v7, v15, v128 op_sel:[0,0,1]
	v_cvt_pk_fp8_f32 v8, v158, v159 op_sel:[0,0,1]
	s_waitcnt lgkmcnt(2)
	v_mfma_scale_f32_32x32x64_f8f6f4 v[160:175], v[194:201], v[184:191], v[160:175], v240, v239 op_sel_hi:[0,0,0]
	v_exp_f32_e32 v129, v140
	v_exp_f32_e32 v130, v141
	v_exp_f32_e32 v131, v142
	v_exp_f32_e32 v132, v143
	v_cvt_pk_fp8_f32 v9, v129, v130
	s_waitcnt lgkmcnt(0)
	v_cvt_pk_fp8_f32 v9, v131, v132 op_sel:[0,0,1]
	v_mfma_scale_f32_32x32x64_f8f6f4 v[112:127], v[246:253], v[184:191], v[112:127], v240, v239 op_sel_hi:[0,0,0]
	s_setprio 0
	s_min_u32 s36, s45, 0x7b
	s_add_i32 s56, s36, 4
	s_lshl_b32 s36, s56, 14
	s_add_i32 s57, s68, 0x4000
	s_add_u32 s88, s94, s36
	s_addc_u32 s89, s95, 0
	s_add_i32 m0, s57, 0x8000
	s_lshl_b32 s36, s56, 13
	s_add_u32 s90, s96, s36
	s_addc_u32 s91, s97, 0
	global_load_lds_dwordx4 v192, s[88:89]
	s_mov_b32 m0, s57
	ds_read_b128 v[194:197], v254 offset:24576
	global_load_lds_dwordx4 v193, s[90:91]
	ds_read_b128 v[148:151], v254 offset:26624
	ds_read_b128 v[198:201], v255 offset:24576
	ds_read_b128 v[152:155], v255 offset:26624
	ds_read_b128 v[136:139], v254 offset:28672
	ds_read_b128 v[128:131], v254 offset:30720
	ds_read_b128 v[140:143], v255 offset:28672
	ds_read_b128 v[132:135], v255 offset:30720
	v_max_f32_e32 v1, v160, v161
	v_max3_f32 v1, v1, v162, v163
	v_max3_f32 v1, v1, v164, v165
	v_max3_f32 v1, v1, v166, v167
	v_max3_f32 v1, v1, v168, v169
	v_max3_f32 v1, v1, v170, v171
	v_max3_f32 v1, v1, v172, v173
	v_max3_f32 v1, v1, v174, v175
	v_max3_f32 v1, v1, v112, v113
	v_max3_f32 v1, v1, v114, v115
	v_max3_f32 v1, v1, v116, v117
	v_max3_f32 v1, v1, v118, v119
	v_max3_f32 v1, v1, v120, v121
	v_max3_f32 v1, v1, v122, v123
	v_max3_f32 v1, v1, v124, v125
	v_max3_f32 v1, v1, v126, v127
	v_cmp_lt_f32_e32 vcc, s80, v1
	s_cbranch_vccnz .LgBc2_384

; #define LAS __attribute__((address_space(3)))
; #define SBAR() __builtin_amdgcn_sched_barrier(0)
; #define WAITV(n) asm volatile("s_waitcnt vmcnt(" #n ")" ::: "memory")
; #define PVL(b) pv_load(vf, V_lds + (b) * SHM_T, vo, e0, e1)
; #define PVM() pv_mma(o, ls, vf, pf)
; #define lane lane_id()
; __device__ __forceinline__ void body(const unsigned char* Q8b, const unsigned char* K8h, const unsigned char* VT8h, const bf16_t* Gb, bf16_t* Ob, int seq, char* lds, const int wid, ...
;     ...
;   PVL((s0 + 1) & 3); finishSM(pB0, pB1, pf); SBAR();
;   PVM();
;   WAITV(0);
;   if (nxt) {
;     load_q(qr, Q8n, wid, r32, hi);
;     const char* KgN = (const char*)K8n + krow * 256 + kc * 16; const char* VgN = (const char*)VT8n + wid * 1024 + lane * 16;
; #pragma unroll
;     for (int tn = 0; tn < 2; ++tn) {
;       __builtin_amdgcn_global_load_lds((const unsigned*)(KgN + (long)tn * (64 * 256)), (LAS unsigned*)(L3 + K_OFF + tn * SHM_T + wid * 1024), 16, 0, 0);
;       __builtin_amdgcn_global_load_lds((const unsigned*)(VgN + (long)tn * 8192), (LAS unsigned*)(L3 + tn * SHM_T + wid * 1024), 16, 0, 0); }
;   }
.LBB0_390:
	v_exp_f32_e32 v13, v100
	v_exp_f32_e32 v14, v101
	v_exp_f32_e32 v12, v99
	v_mov_b32_e32 v99, v0
	v_exp_f32_e32 v15, v102
	v_exp_f32_e32 v100, v103
	v_exp_f32_e32 v102, v104
	v_exp_f32_e32 v103, v105
	v_cvt_pk_fp8_f32 v99, v13, v14
	ds_read_b128 v[144:147], v1 offset:24576
	ds_read_b128 v[136:139], v1 offset:26624
	ds_read_b128 v[148:151], v10 offset:24576
	ds_read_b128 v[140:143], v10 offset:26624
	ds_read_b128 v[128:131], v1 offset:28672
	ds_read_b128 v[2:5], v1 offset:30720
	ds_read_b128 v[132:135], v10 offset:28672
	ds_read_b128 v[6:9], v10 offset:30720
	v_exp_f32_e32 v1, v96
	v_exp_f32_e32 v10, v97
	v_exp_f32_e32 v104, v106
	v_exp_f32_e32 v105, v107
	v_exp_f32_e32 v106, v108
	v_exp_f32_e32 v107, v109
	v_mov_b32_e32 v101, v0
	v_exp_f32_e32 v11, v98
	v_mov_b32_e32 v96, v0
	v_mov_b32_e32 v97, v0
	v_mov_b32_e32 v98, v0
	v_cvt_pk_fp8_f32 v99, v15, v100 op_sel:[0,0,1]
	v_mov_b32_e32 v100, v0
	v_cvt_pk_fp8_f32 v101, v102, v103
	v_mov_b32_e32 v102, v0
	v_mov_b32_e32 v103, v0
	v_exp_f32_e32 v108, v110
	v_exp_f32_e32 v109, v111
	v_cvt_pk_fp8_f32 v96, v112, v113
	v_cvt_pk_fp8_f32 v97, v1, v10
	v_cvt_pk_fp8_f32 v98, v116, v117
	v_cvt_pk_fp8_f32 v100, v120, v121
	v_cvt_pk_fp8_f32 v102, v124, v125
	v_cvt_pk_fp8_f32 v103, v106, v107
	v_cvt_pk_fp8_f32 v96, v114, v115 op_sel:[0,0,1]
	v_cvt_pk_fp8_f32 v97, v11, v12 op_sel:[0,0,1]
	v_cvt_pk_fp8_f32 v98, v118, v119 op_sel:[0,0,1]
	v_cvt_pk_fp8_f32 v100, v122, v123 op_sel:[0,0,1]
	v_cvt_pk_fp8_f32 v101, v104, v105 op_sel:[0,0,1]
	v_cvt_pk_fp8_f32 v102, v126, v127 op_sel:[0,0,1]
	v_cvt_pk_fp8_f32 v103, v108, v109 op_sel:[0,0,1]
	s_waitcnt vmcnt(0)
	s_andn2_b64 vcc, exec, s[54:55]
	s_cbranch_vccnz .LBB0_359
	s_ashr_i32 s45, s44, 31
	s_ashr_i32 s47, s46, 31
	s_lshl_b64 s[56:57], s[44:45], 23
	s_lshl_b64 s[58:59], s[44:45], 21
	s_lshr_b32 s45, s83, 2
	s_lshl_b64 s[54:55], s[46:47], 18
	s_lshl_b32 s36, s83, 7
	s_lshl_b32 s47, s45, 7
	s_add_u32 s53, s63, s54
	s_addc_u32 s54, s64, s55
	s_add_u32 s53, s53, s56
	s_addc_u32 s55, s54, s57
	s_add_u32 s54, s53, s36
	s_addc_u32 s55, s55, 0
	s_add_u32 s36, s65, s58
	s_addc_u32 s53, s66, s59
	s_add_u32 s56, s36, s47
	s_addc_u32 s57, s53, 0
	s_lshl_b32 s36, s44, 1
	v_lshl_add_u64 v[10:11], s[54:55], 0, v[208:209]
	s_or_b32 s58, s36, s45
	v_lshl_add_u64 v[10:11], v[10:11], 0, v[210:211]
	s_ashr_i32 s59, s58, 31
	global_load_dwordx4 v[176:179], v[10:11], off
	global_load_dwordx4 v[180:183], v[10:11], off offset:16
	global_load_dwordx4 v[184:187], v[10:11], off offset:64
	global_load_dwordx4 v[188:191], v[10:11], off offset:80
	v_lshl_add_u64 v[10:11], s[56:57], 0, v[202:203]
	s_mov_b32 m0, s70
	s_lshl_b64 s[58:59], s[58:59], 20
	v_lshl_add_u64 v[10:11], v[10:11], 0, v[204:205]
	v_lshl_add_u64 v[12:13], v[206:207], 0, s[58:59]
	global_load_lds_dwordx4 v[10:11], off
	s_mov_b32 m0, s68
	v_lshl_add_u64 v[10:11], v[10:11], 0, s[38:39]
	global_load_lds_dwordx4 v[12:13], off
	s_mov_b32 m0, s72
	s_nop 0
	global_load_lds_dwordx4 v[10:11], off
	s_mov_b32 m0, s74
	v_lshl_add_u64 v[10:11], v[12:13], 0, s[40:41]
	global_load_lds_dwordx4 v[10:11], off
	s_branch .LBB0_359

; #define PG8_STAGE(bufoff, gbase, voff) do { _Pragma("unroll") for (int _i = 0; _i < 2; ++_i) \
;         __builtin_amdgcn_global_load_lds((const unsigned*)((const char*)(gbase) + (voff)[_i]), (LAS unsigned*)(lds + (bufoff) + ldsw + _i * 8192), 16, 0, 0); } while (0)
; #define PG8_LDA(dst, b, h) do { _Pragma("unroll") for (int m = 0; m < 4; ++m) _Pragma("unroll") for (int k = 0; k < 2; ++k) dst[m][k] = *(const LAS bf16x8*)(lds + PG8_SA(b, h) + aoff + m * 2048 + k * 1024); } while (0)
; #define PG8_LDB(dst, b, h) do { _Pragma("unroll") for (int n = 0; n < 2; ++n) _Pragma("unroll") for (int k = 0; k < 2; ++k) dst[n][k] = *(const LAS bf16x8*)(lds + PG8_SB(b, h) + boff + n * 2048 + k * 1024); } while (0)
; #define PG8_MMA(ai, bj, At, Bt) do { __builtin_amdgcn_s_setprio(1); _Pragma("unroll") for (int m = 0; m < 4; ++m) _Pragma("unroll") for (int n = 0; n < 2; ++n) _Pragma("unroll") for (int k = 0; k < 2; ++k) \
;         acc[ai][bj][m][n] = __builtin_amdgcn_mfma_f32_16x16x32_bf16(Bt[n][k], At[m][k], acc[ai][bj][m][n], 0, 0, 0); __builtin_amdgcn_s_setprio(0); } while (0)
; #define PG8_WAIT_V(n) asm volatile("s_waitcnt vmcnt(" #n ")" ::: "memory")
; #define PG8_WAIT_L(n) asm volatile("s_waitcnt lgkmcnt(" #n ")" ::: "memory")
; #define PG8_BAR __builtin_amdgcn_s_barrier()
; #define PG8_SCHED __builtin_amdgcn_sched_barrier(0)
; template <class Epi, class Sched>
; __device__ __forceinline__ void gemm_phase(LAS unsigned char* lds, const Gemm g, const Sched& S, const Epi& E, const int wid) {
;     ...
;             const bool last = (t == nt - 2);
;             const char* a1 = cA + (size_t)(t + 1) * kstep;
;             const char* a2 = last ? nA : cA + (size_t)(t + 2) * kstep; const char* b2 = last ? nB : cB + (size_t)(t + 2) * kstep;
;             const char* a3 = a2 + kstep; const char* b3 = b2 + kstep;
;             PG8_LDB(B0, 0, 0); PG8_LDB(B1, 0, 1); PG8_SCHED; PG8_LDA(At, 0, 0); PG8_STAGE(PG8_SA(1, 1), a1 + hstepA, voffA);
;             PG8_WAIT_V(8); PG8_WAIT_L(0); PG8_BAR; PG8_MMA(0, 0, At, B0); PG8_MMA(0, 1, At, B1); PG8_BAR; PG8_SCHED;
;             PG8_LDA(At, 0, 1); PG8_STAGE(PG8_SB(0, 0), b2, voffB); PG8_STAGE(PG8_SB(0, 1), b2 + hstepB, voffB); PG8_STAGE(PG8_SA(0, 0), a2, voffA);
;             PG8_WAIT_V(8); PG8_WAIT_L(0); PG8_BAR; PG8_MMA(1, 0, At, B0); PG8_MMA(1, 1, At, B1); PG8_BAR; PG8_SCHED;
.LBB0_459:
	ds_read_b128 v[72:75], v199
	ds_read_b128 v[80:83], v199 offset:1024
	ds_read_b128 v[84:87], v199 offset:2048
	ds_read_b128 v[92:95], v199 offset:3072
	ds_read_b128 v[144:147], v200
	ds_read_b128 v[148:151], v200 offset:1024
	ds_read_b128 v[152:155], v200 offset:2048
	ds_read_b128 v[156:159], v200 offset:3072
	s_add_u32 s56, s54, 0xfffc0080
	s_addc_u32 s57, s55, -1
	s_cmp_eq_u32 s88, 12
	s_cselect_b32 s59, s45, s57
	s_cselect_b32 s58, s51, s56
	s_cselect_b32 s57, s43, s87
	s_cselect_b32 s56, s85, s86
	v_lshl_add_u64 v[210:211], s[54:55], 0, v[164:165]
	s_add_i32 m0, s53, 0xc000
	ds_read_b128 v[172:175], v201
	ds_read_b128 v[176:179], v201 offset:1024
	ds_read_b128 v[180:183], v201 offset:2048
	ds_read_b128 v[184:187], v201 offset:3072
	ds_read_b128 v[188:191], v201 offset:4096
	ds_read_b128 v[192:195], v201 offset:5120
	ds_read_b128 v[202:205], v201 offset:6144
	ds_read_b128 v[206:209], v201 offset:7168
	global_load_lds_dwordx4 v[210:211], off
	s_add_i32 m0, s53, 0xe000
	v_lshl_add_u64 v[210:211], s[54:55], 0, v[166:167]
	global_load_lds_dwordx4 v[210:211], off
	s_waitcnt vmcnt(8)
	s_waitcnt lgkmcnt(0)
	s_barrier
	s_setprio 1
	v_mfma_f32_16x16x32_bf16 v[140:143], v[72:75], v[172:175], v[140:143]
	v_mfma_f32_16x16x32_bf16 v[136:139], v[84:87], v[172:175], v[136:139]
	v_mfma_f32_16x16x32_bf16 v[124:127], v[72:75], v[180:183], v[124:127]
	v_mfma_f32_16x16x32_bf16 v[120:123], v[84:87], v[180:183], v[120:123]
	v_mfma_f32_16x16x32_bf16 v[108:111], v[72:75], v[188:191], v[108:111]
	v_mfma_f32_16x16x32_bf16 v[104:107], v[84:87], v[188:191], v[104:107]
	v_mfma_f32_16x16x32_bf16 v[88:91], v[72:75], v[202:205], v[88:91]
	v_mfma_f32_16x16x32_bf16 v[76:79], v[84:87], v[202:205], v[76:79]
	v_mfma_f32_16x16x32_bf16 v[140:143], v[80:83], v[176:179], v[140:143]
	v_mfma_f32_16x16x32_bf16 v[136:139], v[92:95], v[176:179], v[136:139]
	v_mfma_f32_16x16x32_bf16 v[124:127], v[80:83], v[184:187], v[124:127]
	v_mfma_f32_16x16x32_bf16 v[120:123], v[92:95], v[184:187], v[120:123]
	v_mfma_f32_16x16x32_bf16 v[108:111], v[80:83], v[192:195], v[108:111]
	v_mfma_f32_16x16x32_bf16 v[104:107], v[92:95], v[192:195], v[104:107]
	v_mfma_f32_16x16x32_bf16 v[88:91], v[80:83], v[206:209], v[88:91]
	v_mfma_f32_16x16x32_bf16 v[76:79], v[92:95], v[206:209], v[76:79]
	v_mfma_f32_16x16x32_bf16 v[132:135], v[144:147], v[172:175], v[132:135]
	v_mfma_f32_16x16x32_bf16 v[128:131], v[152:155], v[172:175], v[128:131]
	v_mfma_f32_16x16x32_bf16 v[116:119], v[144:147], v[180:183], v[116:119]
	v_mfma_f32_16x16x32_bf16 v[112:115], v[152:155], v[180:183], v[112:115]
	v_mfma_f32_16x16x32_bf16 v[100:103], v[144:147], v[188:191], v[100:103]
	v_mfma_f32_16x16x32_bf16 v[96:99], v[152:155], v[188:191], v[96:99]
	v_mfma_f32_16x16x32_bf16 v[68:71], v[144:147], v[202:205], v[68:71]
	v_mfma_f32_16x16x32_bf16 v[64:67], v[152:155], v[202:205], v[64:67]
	v_mfma_f32_16x16x32_bf16 v[132:135], v[148:151], v[176:179], v[132:135]
	v_mfma_f32_16x16x32_bf16 v[128:131], v[156:159], v[176:179], v[128:131]
	v_mfma_f32_16x16x32_bf16 v[116:119], v[148:151], v[184:187], v[116:119]
	v_mfma_f32_16x16x32_bf16 v[112:115], v[156:159], v[184:187], v[112:115]
	v_mfma_f32_16x16x32_bf16 v[100:103], v[148:151], v[192:195], v[100:103]
	v_mfma_f32_16x16x32_bf16 v[96:99], v[156:159], v[192:195], v[96:99]
	v_mfma_f32_16x16x32_bf16 v[68:71], v[148:151], v[206:209], v[68:71]
	v_mfma_f32_16x16x32_bf16 v[64:67], v[156:159], v[206:209], v[64:67]
	s_setprio 0
	s_barrier
	s_add_i32 s89, s78, s63
	v_lshl_add_u64 v[210:211], s[56:57], 0, v[160:161]
	s_mov_b32 m0, s89
	ds_read_b128 v[172:175], v201 offset:16384
	ds_read_b128 v[176:179], v201 offset:17408
	ds_read_b128 v[180:183], v201 offset:18432
	ds_read_b128 v[184:187], v201 offset:19456
	ds_read_b128 v[188:191], v201 offset:20480
	ds_read_b128 v[192:195], v201 offset:21504
	ds_read_b128 v[202:205], v201 offset:22528
	ds_read_b128 v[206:209], v201 offset:23552
	global_load_lds_dwordx4 v[210:211], off
	s_add_i32 m0, s89, 0x2000
	s_add_u32 s90, s56, 0x40000
	v_lshl_add_u64 v[212:213], s[56:57], 0, v[162:163]
	s_addc_u32 s91, s57, 0
	s_add_i32 s89, s79, s63
	global_load_lds_dwordx4 v[212:213], off
	v_lshl_add_u64 v[214:215], s[90:91], 0, v[160:161]
	s_mov_b32 m0, s89
	v_lshl_add_u64 v[216:217], s[58:59], 0, v[162:163]
	global_load_lds_dwordx4 v[214:215], off
	s_add_i32 m0, s89, 0x2000
	v_lshl_add_u64 v[214:215], s[90:91], 0, v[162:163]
	global_load_lds_dwordx4 v[214:215], off
	s_mov_b32 m0, s53
	v_lshl_add_u64 v[214:215], s[58:59], 0, v[160:161]
	global_load_lds_dwordx4 v[214:215], off
	s_mov_b32 m0, s64
	s_nop 0
	global_load_lds_dwordx4 v[216:217], off
	s_waitcnt vmcnt(8)
	s_waitcnt lgkmcnt(0)
	s_barrier
; #define PG8_STAGE(bufoff, gbase, voff) do { _Pragma("unroll") for (int _i = 0; _i < 2; ++_i) \
;         __builtin_amdgcn_global_load_lds((const unsigned*)((const char*)(gbase) + (voff)[_i]), (LAS unsigned*)(lds + (bufoff) + ldsw + _i * 8192), 16, 0, 0); } while (0)
; #define PG8_LDA(dst, b, h) do { _Pragma("unroll") for (int m = 0; m < 4; ++m) _Pragma("unroll") for (int k = 0; k < 2; ++k) dst[m][k] = *(const LAS bf16x8*)(lds + PG8_SA(b, h) + aoff + m * 2048 + k * 1024); } while (0)
; #define PG8_LDB(dst, b, h) do { _Pragma("unroll") for (int n = 0; n < 2; ++n) _Pragma("unroll") for (int k = 0; k < 2; ++k) dst[n][k] = *(const LAS bf16x8*)(lds + PG8_SB(b, h) + boff + n * 2048 + k * 1024); } while (0)
; #define PG8_MMA(ai, bj, At, Bt) do { __builtin_amdgcn_s_setprio(1); _Pragma("unroll") for (int m = 0; m < 4; ++m) _Pragma("unroll") for (int n = 0; n < 2; ++n) _Pragma("unroll") for (int k = 0; k < 2; ++k) \
;         acc[ai][bj][m][n] = __builtin_amdgcn_mfma_f32_16x16x32_bf16(Bt[n][k], At[m][k], acc[ai][bj][m][n], 0, 0, 0); __builtin_amdgcn_s_setprio(0); } while (0)
; #define PG8_WAIT_V(n) asm volatile("s_waitcnt vmcnt(" #n ")" ::: "memory")
; #define PG8_WAIT_L(n) asm volatile("s_waitcnt lgkmcnt(" #n ")" ::: "memory")
; #define PG8_BAR __builtin_amdgcn_s_barrier()
; #define PG8_SCHED __builtin_amdgcn_sched_barrier(0)
; template <class Epi, class Sched>
; __device__ __forceinline__ void gemm_phase(LAS unsigned char* lds, const Gemm g, const Sched& S, const Epi& E, const int wid) {
;     ...
;             PG8_WAIT_V(8); PG8_WAIT_L(0); PG8_BAR; PG8_MMA(1, 0, At, B0); PG8_MMA(1, 1, At, B1); PG8_BAR; PG8_SCHED;
;             PG8_LDB(B0, 1, 0); PG8_LDB(B1, 1, 1); PG8_SCHED; PG8_LDA(At, 1, 0); PG8_STAGE(PG8_SA(0, 1), a2 + hstepA, voffA);
;             PG8_WAIT_V(8); PG8_WAIT_L(0); PG8_BAR; PG8_MMA(0, 0, At, B0); PG8_MMA(0, 1, At, B1); PG8_BAR; PG8_SCHED;
	s_setprio 1
	v_mfma_f32_16x16x32_bf16 v[60:63], v[72:75], v[172:175], v[60:63]
	v_mfma_f32_16x16x32_bf16 v[56:59], v[84:87], v[172:175], v[56:59]
	v_mfma_f32_16x16x32_bf16 v[44:47], v[72:75], v[180:183], v[44:47]
	v_mfma_f32_16x16x32_bf16 v[40:43], v[84:87], v[180:183], v[40:43]
	v_mfma_f32_16x16x32_bf16 v[28:31], v[72:75], v[188:191], v[28:31]
	v_mfma_f32_16x16x32_bf16 v[24:27], v[84:87], v[188:191], v[24:27]
	v_mfma_f32_16x16x32_bf16 v[12:15], v[72:75], v[202:205], v[12:15]
	v_mfma_f32_16x16x32_bf16 v[8:11], v[84:87], v[202:205], v[8:11]
	v_mfma_f32_16x16x32_bf16 v[60:63], v[80:83], v[176:179], v[60:63]
	v_mfma_f32_16x16x32_bf16 v[56:59], v[92:95], v[176:179], v[56:59]
	v_mfma_f32_16x16x32_bf16 v[44:47], v[80:83], v[184:187], v[44:47]
	v_mfma_f32_16x16x32_bf16 v[40:43], v[92:95], v[184:187], v[40:43]
	v_mfma_f32_16x16x32_bf16 v[28:31], v[80:83], v[192:195], v[28:31]
	v_mfma_f32_16x16x32_bf16 v[24:27], v[92:95], v[192:195], v[24:27]
	v_mfma_f32_16x16x32_bf16 v[12:15], v[80:83], v[206:209], v[12:15]
	v_mfma_f32_16x16x32_bf16 v[8:11], v[92:95], v[206:209], v[8:11]
	v_mfma_f32_16x16x32_bf16 v[52:55], v[144:147], v[172:175], v[52:55]
	v_mfma_f32_16x16x32_bf16 v[48:51], v[152:155], v[172:175], v[48:51]
	v_mfma_f32_16x16x32_bf16 v[36:39], v[144:147], v[180:183], v[36:39]
	v_mfma_f32_16x16x32_bf16 v[32:35], v[152:155], v[180:183], v[32:35]
	v_mfma_f32_16x16x32_bf16 v[20:23], v[144:147], v[188:191], v[20:23]
	v_mfma_f32_16x16x32_bf16 v[16:19], v[152:155], v[188:191], v[16:19]
	v_mfma_f32_16x16x32_bf16 v[4:7], v[144:147], v[202:205], v[4:7]
	v_mfma_f32_16x16x32_bf16 v[0:3], v[152:155], v[202:205], v[0:3]
	v_mfma_f32_16x16x32_bf16 v[52:55], v[148:151], v[176:179], v[52:55]
	v_mfma_f32_16x16x32_bf16 v[48:51], v[156:159], v[176:179], v[48:51]
	v_mfma_f32_16x16x32_bf16 v[36:39], v[148:151], v[184:187], v[36:39]
	v_mfma_f32_16x16x32_bf16 v[32:35], v[156:159], v[184:187], v[32:35]
	v_mfma_f32_16x16x32_bf16 v[20:23], v[148:151], v[192:195], v[20:23]
	v_mfma_f32_16x16x32_bf16 v[16:19], v[156:159], v[192:195], v[16:19]
	v_mfma_f32_16x16x32_bf16 v[4:7], v[148:151], v[206:209], v[4:7]
	v_mfma_f32_16x16x32_bf16 v[0:3], v[156:159], v[206:209], v[0:3]
	s_setprio 0
	s_barrier
	s_add_i32 s89, 0, 0x18000
	s_add_i32 s90, 0, 0x1c000
	v_add_u32_e32 v92, s89, v197
	v_add_u32_e32 v156, s90, v197
	ds_read_b128 v[72:75], v92
	ds_read_b128 v[80:83], v92 offset:1024
	ds_read_b128 v[84:87], v92 offset:2048
	ds_read_b128 v[92:95], v92 offset:3072
	ds_read_b128 v[144:147], v156
	ds_read_b128 v[148:151], v156 offset:1024
	ds_read_b128 v[152:155], v156 offset:2048
	ds_read_b128 v[156:159], v156 offset:3072
	s_add_u32 s58, s58, 0x40000
	s_addc_u32 s59, s59, 0
	s_mov_b32 m0, s65
	v_lshl_add_u64 v[218:219], s[58:59], 0, v[160:161]
	ds_read_b128 v[172:175], v201 offset:32768
	ds_read_b128 v[176:179], v201 offset:33792
	ds_read_b128 v[180:183], v201 offset:34816
	ds_read_b128 v[184:187], v201 offset:35840
	ds_read_b128 v[188:191], v201 offset:36864
	ds_read_b128 v[192:195], v201 offset:37888
	ds_read_b128 v[202:205], v201 offset:38912
	ds_read_b128 v[206:209], v201 offset:39936
	global_load_lds_dwordx4 v[218:219], off
	s_mov_b32 m0, s66
	v_lshl_add_u64 v[218:219], s[58:59], 0, v[162:163]
	global_load_lds_dwordx4 v[218:219], off
	s_waitcnt vmcnt(8)
	s_waitcnt lgkmcnt(0)
	s_barrier
	s_setprio 1
	v_mfma_f32_16x16x32_bf16 v[140:143], v[72:75], v[172:175], v[140:143]
	v_mfma_f32_16x16x32_bf16 v[136:139], v[84:87], v[172:175], v[136:139]
	v_mfma_f32_16x16x32_bf16 v[124:127], v[72:75], v[180:183], v[124:127]
	v_mfma_f32_16x16x32_bf16 v[120:123], v[84:87], v[180:183], v[120:123]
	v_mfma_f32_16x16x32_bf16 v[108:111], v[72:75], v[188:191], v[108:111]
	v_mfma_f32_16x16x32_bf16 v[104:107], v[84:87], v[188:191], v[104:107]
	v_mfma_f32_16x16x32_bf16 v[88:91], v[72:75], v[202:205], v[88:91]
	v_mfma_f32_16x16x32_bf16 v[76:79], v[84:87], v[202:205], v[76:79]
	v_mfma_f32_16x16x32_bf16 v[140:143], v[80:83], v[176:179], v[140:143]
	v_mfma_f32_16x16x32_bf16 v[136:139], v[92:95], v[176:179], v[136:139]
	v_mfma_f32_16x16x32_bf16 v[124:127], v[80:83], v[184:187], v[124:127]
	v_mfma_f32_16x16x32_bf16 v[120:123], v[92:95], v[184:187], v[120:123]
	v_mfma_f32_16x16x32_bf16 v[108:111], v[80:83], v[192:195], v[108:111]
	v_mfma_f32_16x16x32_bf16 v[104:107], v[92:95], v[192:195], v[104:107]
	v_mfma_f32_16x16x32_bf16 v[88:91], v[80:83], v[206:209], v[88:91]
	v_mfma_f32_16x16x32_bf16 v[76:79], v[92:95], v[206:209], v[76:79]
	v_mfma_f32_16x16x32_bf16 v[132:135], v[144:147], v[172:175], v[132:135]
	v_mfma_f32_16x16x32_bf16 v[128:131], v[152:155], v[172:175], v[128:131]
	v_mfma_f32_16x16x32_bf16 v[116:119], v[144:147], v[180:183], v[116:119]
	v_mfma_f32_16x16x32_bf16 v[112:115], v[152:155], v[180:183], v[112:115]
	v_mfma_f32_16x16x32_bf16 v[100:103], v[144:147], v[188:191], v[100:103]
	v_mfma_f32_16x16x32_bf16 v[96:99], v[152:155], v[188:191], v[96:99]
	v_mfma_f32_16x16x32_bf16 v[68:71], v[144:147], v[202:205], v[68:71]
	v_mfma_f32_16x16x32_bf16 v[64:67], v[152:155], v[202:205], v[64:67]
	v_mfma_f32_16x16x32_bf16 v[132:135], v[148:151], v[176:179], v[132:135]
	v_mfma_f32_16x16x32_bf16 v[128:131], v[156:159], v[176:179], v[128:131]
	v_mfma_f32_16x16x32_bf16 v[116:119], v[148:151], v[184:187], v[116:119]
	v_mfma_f32_16x16x32_bf16 v[112:115], v[156:159], v[184:187], v[112:115]
	v_mfma_f32_16x16x32_bf16 v[100:103], v[148:151], v[192:195], v[100:103]
	v_mfma_f32_16x16x32_bf16 v[96:99], v[156:159], v[192:195], v[96:99]
	v_mfma_f32_16x16x32_bf16 v[68:71], v[148:151], v[206:209], v[68:71]
	v_mfma_f32_16x16x32_bf16 v[64:67], v[156:159], v[206:209], v[64:67]
	s_setprio 0
	s_barrier
; #define PG8_STAGE(bufoff, gbase, voff) do { _Pragma("unroll") for (int _i = 0; _i < 2; ++_i) \
;         __builtin_amdgcn_global_load_lds((const unsigned*)((const char*)(gbase) + (voff)[_i]), (LAS unsigned*)(lds + (bufoff) + ldsw + _i * 8192), 16, 0, 0); } while (0)
; #define PG8_LDA(dst, b, h) do { _Pragma("unroll") for (int m = 0; m < 4; ++m) _Pragma("unroll") for (int k = 0; k < 2; ++k) dst[m][k] = *(const LAS bf16x8*)(lds + PG8_SA(b, h) + aoff + m * 2048 + k * 1024); } while (0)
; #define PG8_MMA(ai, bj, At, Bt) do { __builtin_amdgcn_s_setprio(1); _Pragma("unroll") for (int m = 0; m < 4; ++m) _Pragma("unroll") for (int n = 0; n < 2; ++n) _Pragma("unroll") for (int k = 0; k < 2; ++k) \
;         acc[ai][bj][m][n] = __builtin_amdgcn_mfma_f32_16x16x32_bf16(Bt[n][k], At[m][k], acc[ai][bj][m][n], 0, 0, 0); __builtin_amdgcn_s_setprio(0); } while (0)
; #define PG8_WAIT_V(n) asm volatile("s_waitcnt vmcnt(" #n ")" ::: "memory")
; #define PG8_WAIT_L(n) asm volatile("s_waitcnt lgkmcnt(" #n ")" ::: "memory")
; #define PG8_BAR __builtin_amdgcn_s_barrier()
; #define PG8_SCHED __builtin_amdgcn_sched_barrier(0)
; template <class Epi, class Sched>
; __device__ __forceinline__ void gemm_phase(LAS unsigned char* lds, const Gemm g, const Sched& S, const Epi& E, const int wid) {
;     ...
;             PG8_LDA(At, 1, 1); PG8_STAGE(PG8_SB(1, 0), b3, voffB); PG8_STAGE(PG8_SB(1, 1), b3 + hstepB, voffB); PG8_STAGE(PG8_SA(1, 0), a3, voffA);
;             PG8_WAIT_V(8); PG8_WAIT_L(0); PG8_BAR; PG8_MMA(1, 0, At, B0); PG8_MMA(1, 1, At, B1); PG8_BAR; PG8_SCHED;
;         }
;         if (wr == 0) PG8_BAR;
	s_add_i32 s58, s89, s63
	v_lshl_add_u64 v[210:211], v[210:211], 0, s[34:35]
	s_mov_b32 m0, s58
	ds_read_b128 v[172:175], v201 offset:49152
	ds_read_b128 v[176:179], v201 offset:50176
	ds_read_b128 v[180:183], v201 offset:51200
	ds_read_b128 v[184:187], v201 offset:52224
	ds_read_b128 v[188:191], v201 offset:53248
	ds_read_b128 v[192:195], v201 offset:54272
	ds_read_b128 v[202:205], v201 offset:55296
	ds_read_b128 v[206:209], v201 offset:56320
	global_load_lds_dwordx4 v[210:211], off
	s_add_i32 m0, s58, 0x2000
	s_add_u32 s56, s56, 0x40080
	v_lshl_add_u64 v[210:211], v[212:213], 0, s[34:35]
	s_addc_u32 s57, s57, 0
	s_add_i32 s58, s90, s63
	global_load_lds_dwordx4 v[210:211], off
	s_mov_b32 m0, s58
	v_lshl_add_u64 v[210:211], s[56:57], 0, v[160:161]
	global_load_lds_dwordx4 v[210:211], off
	s_add_i32 m0, s58, 0x2000
	v_lshl_add_u64 v[210:211], s[56:57], 0, v[162:163]
	global_load_lds_dwordx4 v[210:211], off
	s_mov_b32 m0, s72
	v_lshl_add_u64 v[210:211], v[214:215], 0, s[34:35]
	global_load_lds_dwordx4 v[210:211], off
	s_mov_b32 m0, s73
	v_lshl_add_u64 v[210:211], v[216:217], 0, s[34:35]
	global_load_lds_dwordx4 v[210:211], off
	s_waitcnt vmcnt(8)
	s_waitcnt lgkmcnt(0)
	s_barrier
	s_setprio 1
	v_mfma_f32_16x16x32_bf16 v[60:63], v[72:75], v[172:175], v[60:63]
	v_mfma_f32_16x16x32_bf16 v[56:59], v[84:87], v[172:175], v[56:59]
	v_mfma_f32_16x16x32_bf16 v[44:47], v[72:75], v[180:183], v[44:47]
	v_mfma_f32_16x16x32_bf16 v[40:43], v[84:87], v[180:183], v[40:43]
	v_mfma_f32_16x16x32_bf16 v[28:31], v[72:75], v[188:191], v[28:31]
	v_mfma_f32_16x16x32_bf16 v[24:27], v[84:87], v[188:191], v[24:27]
	v_mfma_f32_16x16x32_bf16 v[12:15], v[72:75], v[202:205], v[12:15]
	v_mfma_f32_16x16x32_bf16 v[8:11], v[84:87], v[202:205], v[8:11]
	v_mfma_f32_16x16x32_bf16 v[60:63], v[80:83], v[176:179], v[60:63]
	v_mfma_f32_16x16x32_bf16 v[56:59], v[92:95], v[176:179], v[56:59]
	v_mfma_f32_16x16x32_bf16 v[44:47], v[80:83], v[184:187], v[44:47]
	v_mfma_f32_16x16x32_bf16 v[40:43], v[92:95], v[184:187], v[40:43]
	v_mfma_f32_16x16x32_bf16 v[28:31], v[80:83], v[192:195], v[28:31]
	v_mfma_f32_16x16x32_bf16 v[24:27], v[92:95], v[192:195], v[24:27]
	v_mfma_f32_16x16x32_bf16 v[12:15], v[80:83], v[206:209], v[12:15]
	v_mfma_f32_16x16x32_bf16 v[8:11], v[92:95], v[206:209], v[8:11]
	v_mfma_f32_16x16x32_bf16 v[52:55], v[144:147], v[172:175], v[52:55]
	v_mfma_f32_16x16x32_bf16 v[48:51], v[152:155], v[172:175], v[48:51]
	v_mfma_f32_16x16x32_bf16 v[36:39], v[144:147], v[180:183], v[36:39]
	v_mfma_f32_16x16x32_bf16 v[32:35], v[152:155], v[180:183], v[32:35]
	v_mfma_f32_16x16x32_bf16 v[20:23], v[144:147], v[188:191], v[20:23]
	v_mfma_f32_16x16x32_bf16 v[16:19], v[152:155], v[188:191], v[16:19]
	v_mfma_f32_16x16x32_bf16 v[4:7], v[144:147], v[202:205], v[4:7]
	v_mfma_f32_16x16x32_bf16 v[0:3], v[152:155], v[202:205], v[0:3]
	v_mfma_f32_16x16x32_bf16 v[52:55], v[148:151], v[176:179], v[52:55]
	v_mfma_f32_16x16x32_bf16 v[48:51], v[156:159], v[176:179], v[48:51]
	v_mfma_f32_16x16x32_bf16 v[36:39], v[148:151], v[184:187], v[36:39]
	v_mfma_f32_16x16x32_bf16 v[32:35], v[156:159], v[184:187], v[32:35]
	v_mfma_f32_16x16x32_bf16 v[20:23], v[148:151], v[192:195], v[20:23]
	v_mfma_f32_16x16x32_bf16 v[16:19], v[156:159], v[192:195], v[16:19]
	v_mfma_f32_16x16x32_bf16 v[4:7], v[148:151], v[206:209], v[4:7]
	v_mfma_f32_16x16x32_bf16 v[0:3], v[156:159], v[206:209], v[0:3]
	s_setprio 0
	s_barrier
	s_add_i32 s88, s88, 2
	s_add_u32 s54, s54, 0x100
	s_addc_u32 s55, s55, 0
	s_add_u32 s86, s86, 0x100
	s_addc_u32 s87, s87, 0
	s_cmp_gt_u32 s88, 13
	s_cbranch_scc0 .LBB0_459
	s_and_b64 vcc, exec, s[38:39]
	s_cbranch_vccz .LBB0_462
	s_barrier

; #define PG8_STAGE(bufoff, gbase, voff) do { _Pragma("unroll") for (int _i = 0; _i < 2; ++_i) \
;         __builtin_amdgcn_global_load_lds((const unsigned*)((const char*)(gbase) + (voff)[_i]), (LAS unsigned*)(lds + (bufoff) + ldsw + _i * 8192), 16, 0, 0); } while (0)
; #define PG8_LDA(dst, b, h) do { _Pragma("unroll") for (int m = 0; m < 4; ++m) _Pragma("unroll") for (int k = 0; k < 2; ++k) dst[m][k] = *(const LAS bf16x8*)(lds + PG8_SA(b, h) + aoff + m * 2048 + k * 1024); } while (0)
; #define PG8_LDB(dst, b, h) do { _Pragma("unroll") for (int n = 0; n < 2; ++n) _Pragma("unroll") for (int k = 0; k < 2; ++k) dst[n][k] = *(const LAS bf16x8*)(lds + PG8_SB(b, h) + boff + n * 2048 + k * 1024); } while (0)
; #define PG8_MMA(ai, bj, At, Bt) do { __builtin_amdgcn_s_setprio(1); _Pragma("unroll") for (int m = 0; m < 4; ++m) _Pragma("unroll") for (int n = 0; n < 2; ++n) _Pragma("unroll") for (int k = 0; k < 2; ++k) \
;         acc[ai][bj][m][n] = __builtin_amdgcn_mfma_f32_16x16x32_bf16(Bt[n][k], At[m][k], acc[ai][bj][m][n], 0, 0, 0); __builtin_amdgcn_s_setprio(0); } while (0)
; #define PG8_WAIT_V(n) asm volatile("s_waitcnt vmcnt(" #n ")" ::: "memory")
; #define PG8_WAIT_L(n) asm volatile("s_waitcnt lgkmcnt(" #n ")" ::: "memory")
; #define PG8_BAR __builtin_amdgcn_s_barrier()
; #define PG8_SCHED __builtin_amdgcn_sched_barrier(0)
; template <class Epi, class Sched>
; __device__ __forceinline__ void gemm_phase(LAS unsigned char* lds, const Gemm g, const Sched& S, const Epi& E, const int wid) {
;     ...
;             const bool last = (t == nt - 2);
;             const char* a1 = cA + (size_t)(t + 1) * kstep;
;             const char* a2 = last ? nA : cA + (size_t)(t + 2) * kstep; const char* b2 = last ? nB : cB + (size_t)(t + 2) * kstep;
;             const char* a3 = a2 + kstep; const char* b3 = b2 + kstep;
;             PG8_LDB(B0, 0, 0); PG8_LDB(B1, 0, 1); PG8_SCHED; PG8_LDA(At, 0, 0); PG8_STAGE(PG8_SA(1, 1), a1 + hstepA, voffA);
;             PG8_WAIT_V(8); PG8_WAIT_L(0); PG8_BAR; PG8_MMA(0, 0, At, B0); PG8_MMA(0, 1, At, B1); PG8_BAR; PG8_SCHED;
;             PG8_LDA(At, 0, 1); PG8_STAGE(PG8_SB(0, 0), b2, voffB); PG8_STAGE(PG8_SB(0, 1), b2 + hstepB, voffB); PG8_STAGE(PG8_SA(0, 0), a2, voffA);
;             PG8_WAIT_V(8); PG8_WAIT_L(0); PG8_BAR; PG8_MMA(1, 0, At, B0); PG8_MMA(1, 1, At, B1); PG8_BAR; PG8_SCHED;
.LBB0_546:
	ds_read_b128 v[128:131], v167
	ds_read_b128 v[132:135], v167 offset:1024
	ds_read_b128 v[136:139], v167 offset:2048
	ds_read_b128 v[140:143], v167 offset:3072
	ds_read_b128 v[172:175], v168
	ds_read_b128 v[176:179], v168 offset:1024
	ds_read_b128 v[180:183], v168 offset:2048
	ds_read_b128 v[184:187], v168 offset:3072
	s_add_u32 s48, s46, 0xfffc0080
	s_addc_u32 s49, s47, -1
	s_cmp_eq_u32 s81, 12
	s_cselect_b32 s51, s39, s49
	s_cselect_b32 s50, s77, s48
	s_cselect_b32 s49, s37, s80
	s_cselect_b32 s48, s78, s79
	v_lshl_add_u64 v[164:165], s[46:47], 0, v[156:157]
	s_add_i32 m0, s57, 0xc000
	ds_read_b128 v[188:191], v169
	ds_read_b128 v[192:195], v169 offset:1024
	ds_read_b128 v[196:199], v169 offset:2048
	ds_read_b128 v[200:203], v169 offset:3072
	ds_read_b128 v[204:207], v169 offset:4096
	ds_read_b128 v[208:211], v169 offset:5120
	ds_read_b128 v[212:215], v169 offset:6144
	ds_read_b128 v[216:219], v169 offset:7168
	global_load_lds_dwordx4 v[164:165], off
	s_add_i32 m0, s57, 0xe000
	v_lshl_add_u64 v[164:165], s[46:47], 0, v[158:159]
	global_load_lds_dwordx4 v[164:165], off
	s_waitcnt vmcnt(8)
	s_waitcnt lgkmcnt(0)
	s_barrier
	s_setprio 1
	v_mfma_f32_16x16x32_bf16 v[124:127], v[128:131], v[188:191], v[124:127]
	v_mfma_f32_16x16x32_bf16 v[120:123], v[136:139], v[188:191], v[120:123]
	v_mfma_f32_16x16x32_bf16 v[116:119], v[128:131], v[196:199], v[116:119]
	v_mfma_f32_16x16x32_bf16 v[112:115], v[136:139], v[196:199], v[112:115]
	v_mfma_f32_16x16x32_bf16 v[108:111], v[128:131], v[204:207], v[108:111]
	v_mfma_f32_16x16x32_bf16 v[96:99], v[136:139], v[204:207], v[96:99]
	v_mfma_f32_16x16x32_bf16 v[80:83], v[128:131], v[212:215], v[80:83]
	v_mfma_f32_16x16x32_bf16 v[72:75], v[136:139], v[212:215], v[72:75]
	v_mfma_f32_16x16x32_bf16 v[124:127], v[132:135], v[192:195], v[124:127]
	v_mfma_f32_16x16x32_bf16 v[120:123], v[140:143], v[192:195], v[120:123]
	v_mfma_f32_16x16x32_bf16 v[116:119], v[132:135], v[200:203], v[116:119]
	v_mfma_f32_16x16x32_bf16 v[112:115], v[140:143], v[200:203], v[112:115]
	v_mfma_f32_16x16x32_bf16 v[108:111], v[132:135], v[208:211], v[108:111]
	v_mfma_f32_16x16x32_bf16 v[96:99], v[140:143], v[208:211], v[96:99]
	v_mfma_f32_16x16x32_bf16 v[80:83], v[132:135], v[216:219], v[80:83]
	v_mfma_f32_16x16x32_bf16 v[72:75], v[140:143], v[216:219], v[72:75]
	v_mfma_f32_16x16x32_bf16 v[104:107], v[172:175], v[188:191], v[104:107]
	v_mfma_f32_16x16x32_bf16 v[100:103], v[180:183], v[188:191], v[100:103]
	v_mfma_f32_16x16x32_bf16 v[92:95], v[172:175], v[196:199], v[92:95]
	v_mfma_f32_16x16x32_bf16 v[88:91], v[180:183], v[196:199], v[88:91]
	v_mfma_f32_16x16x32_bf16 v[84:87], v[172:175], v[204:207], v[84:87]
	v_mfma_f32_16x16x32_bf16 v[76:79], v[180:183], v[204:207], v[76:79]
	v_mfma_f32_16x16x32_bf16 v[68:71], v[172:175], v[212:215], v[68:71]
	v_mfma_f32_16x16x32_bf16 v[64:67], v[180:183], v[212:215], v[64:67]
	v_mfma_f32_16x16x32_bf16 v[104:107], v[176:179], v[192:195], v[104:107]
	v_mfma_f32_16x16x32_bf16 v[100:103], v[184:187], v[192:195], v[100:103]
	v_mfma_f32_16x16x32_bf16 v[92:95], v[176:179], v[200:203], v[92:95]
	v_mfma_f32_16x16x32_bf16 v[88:91], v[184:187], v[200:203], v[88:91]
	v_mfma_f32_16x16x32_bf16 v[84:87], v[176:179], v[208:211], v[84:87]
	v_mfma_f32_16x16x32_bf16 v[76:79], v[184:187], v[208:211], v[76:79]
	v_mfma_f32_16x16x32_bf16 v[68:71], v[176:179], v[216:219], v[68:71]
	v_mfma_f32_16x16x32_bf16 v[64:67], v[184:187], v[216:219], v[64:67]
	s_setprio 0
	s_barrier
	s_add_i32 s82, s70, s54
	v_lshl_add_u64 v[164:165], s[48:49], 0, v[148:149]
	s_mov_b32 m0, s82
	ds_read_b128 v[188:191], v169 offset:16384
	ds_read_b128 v[192:195], v169 offset:17408
	ds_read_b128 v[196:199], v169 offset:18432
	ds_read_b128 v[200:203], v169 offset:19456
	ds_read_b128 v[204:207], v169 offset:20480
	ds_read_b128 v[208:211], v169 offset:21504
	ds_read_b128 v[212:215], v169 offset:22528
	ds_read_b128 v[216:219], v169 offset:23552
	global_load_lds_dwordx4 v[164:165], off
	s_add_i32 m0, s82, 0x2000
	s_add_u32 s82, s48, 0x40000
	v_lshl_add_u64 v[220:221], s[48:49], 0, v[144:145]
	s_addc_u32 s83, s49, 0
	s_add_i32 s84, s71, s54
	global_load_lds_dwordx4 v[220:221], off
	v_lshl_add_u64 v[222:223], s[82:83], 0, v[148:149]
	s_mov_b32 m0, s84
	v_lshl_add_u64 v[224:225], s[50:51], 0, v[146:147]
	global_load_lds_dwordx4 v[222:223], off
	s_add_i32 m0, s84, 0x2000
	v_lshl_add_u64 v[222:223], s[82:83], 0, v[144:145]
	global_load_lds_dwordx4 v[222:223], off
	s_mov_b32 m0, s57
	v_lshl_add_u64 v[222:223], s[50:51], 0, v[150:151]
	global_load_lds_dwordx4 v[222:223], off
	s_mov_b32 m0, s58
	s_nop 0
	global_load_lds_dwordx4 v[224:225], off
	s_waitcnt vmcnt(8)
	s_waitcnt lgkmcnt(0)
	s_barrier
; #define PG8_STAGE(bufoff, gbase, voff) do { _Pragma("unroll") for (int _i = 0; _i < 2; ++_i) \
;         __builtin_amdgcn_global_load_lds((const unsigned*)((const char*)(gbase) + (voff)[_i]), (LAS unsigned*)(lds + (bufoff) + ldsw + _i * 8192), 16, 0, 0); } while (0)
; #define PG8_LDA(dst, b, h) do { _Pragma("unroll") for (int m = 0; m < 4; ++m) _Pragma("unroll") for (int k = 0; k < 2; ++k) dst[m][k] = *(const LAS bf16x8*)(lds + PG8_SA(b, h) + aoff + m * 2048 + k * 1024); } while (0)
; #define PG8_LDB(dst, b, h) do { _Pragma("unroll") for (int n = 0; n < 2; ++n) _Pragma("unroll") for (int k = 0; k < 2; ++k) dst[n][k] = *(const LAS bf16x8*)(lds + PG8_SB(b, h) + boff + n * 2048 + k * 1024); } while (0)
; #define PG8_MMA(ai, bj, At, Bt) do { __builtin_amdgcn_s_setprio(1); _Pragma("unroll") for (int m = 0; m < 4; ++m) _Pragma("unroll") for (int n = 0; n < 2; ++n) _Pragma("unroll") for (int k = 0; k < 2; ++k) \
;         acc[ai][bj][m][n] = __builtin_amdgcn_mfma_f32_16x16x32_bf16(Bt[n][k], At[m][k], acc[ai][bj][m][n], 0, 0, 0); __builtin_amdgcn_s_setprio(0); } while (0)
; #define PG8_WAIT_V(n) asm volatile("s_waitcnt vmcnt(" #n ")" ::: "memory")
; #define PG8_WAIT_L(n) asm volatile("s_waitcnt lgkmcnt(" #n ")" ::: "memory")
; #define PG8_BAR __builtin_amdgcn_s_barrier()
; #define PG8_SCHED __builtin_amdgcn_sched_barrier(0)
; template <class Epi, class Sched>
; __device__ __forceinline__ void gemm_phase(LAS unsigned char* lds, const Gemm g, const Sched& S, const Epi& E, const int wid) {
;     ...
;             PG8_WAIT_V(8); PG8_WAIT_L(0); PG8_BAR; PG8_MMA(1, 0, At, B0); PG8_MMA(1, 1, At, B1); PG8_BAR; PG8_SCHED;
;             PG8_LDB(B0, 1, 0); PG8_LDB(B1, 1, 1); PG8_SCHED; PG8_LDA(At, 1, 0); PG8_STAGE(PG8_SA(0, 1), a2 + hstepA, voffA);
;             PG8_WAIT_V(8); PG8_WAIT_L(0); PG8_BAR; PG8_MMA(0, 0, At, B0); PG8_MMA(0, 1, At, B1); PG8_BAR; PG8_SCHED;
	s_setprio 1
	v_mfma_f32_16x16x32_bf16 v[60:63], v[128:131], v[188:191], v[60:63]
	v_mfma_f32_16x16x32_bf16 v[56:59], v[136:139], v[188:191], v[56:59]
	v_mfma_f32_16x16x32_bf16 v[48:51], v[128:131], v[196:199], v[48:51]
	v_mfma_f32_16x16x32_bf16 v[40:43], v[136:139], v[196:199], v[40:43]
	v_mfma_f32_16x16x32_bf16 v[32:35], v[128:131], v[204:207], v[32:35]
	v_mfma_f32_16x16x32_bf16 v[24:27], v[136:139], v[204:207], v[24:27]
	v_mfma_f32_16x16x32_bf16 v[16:19], v[128:131], v[212:215], v[16:19]
	v_mfma_f32_16x16x32_bf16 v[8:11], v[136:139], v[212:215], v[8:11]
	v_mfma_f32_16x16x32_bf16 v[60:63], v[132:135], v[192:195], v[60:63]
	v_mfma_f32_16x16x32_bf16 v[56:59], v[140:143], v[192:195], v[56:59]
	v_mfma_f32_16x16x32_bf16 v[48:51], v[132:135], v[200:203], v[48:51]
	v_mfma_f32_16x16x32_bf16 v[40:43], v[140:143], v[200:203], v[40:43]
	v_mfma_f32_16x16x32_bf16 v[32:35], v[132:135], v[208:211], v[32:35]
	v_mfma_f32_16x16x32_bf16 v[24:27], v[140:143], v[208:211], v[24:27]
	v_mfma_f32_16x16x32_bf16 v[16:19], v[132:135], v[216:219], v[16:19]
	v_mfma_f32_16x16x32_bf16 v[8:11], v[140:143], v[216:219], v[8:11]
	v_mfma_f32_16x16x32_bf16 v[52:55], v[172:175], v[188:191], v[52:55]
	v_mfma_f32_16x16x32_bf16 v[44:47], v[180:183], v[188:191], v[44:47]
	v_mfma_f32_16x16x32_bf16 v[36:39], v[172:175], v[196:199], v[36:39]
	v_mfma_f32_16x16x32_bf16 v[28:31], v[180:183], v[196:199], v[28:31]
	v_mfma_f32_16x16x32_bf16 v[20:23], v[172:175], v[204:207], v[20:23]
	v_mfma_f32_16x16x32_bf16 v[12:15], v[180:183], v[204:207], v[12:15]
	v_mfma_f32_16x16x32_bf16 v[4:7], v[172:175], v[212:215], v[4:7]
	v_mfma_f32_16x16x32_bf16 v[0:3], v[180:183], v[212:215], v[0:3]
	v_mfma_f32_16x16x32_bf16 v[52:55], v[176:179], v[192:195], v[52:55]
	v_mfma_f32_16x16x32_bf16 v[44:47], v[184:187], v[192:195], v[44:47]
	v_mfma_f32_16x16x32_bf16 v[36:39], v[176:179], v[200:203], v[36:39]
	v_mfma_f32_16x16x32_bf16 v[28:31], v[184:187], v[200:203], v[28:31]
	v_mfma_f32_16x16x32_bf16 v[20:23], v[176:179], v[208:211], v[20:23]
	v_mfma_f32_16x16x32_bf16 v[12:15], v[184:187], v[208:211], v[12:15]
	v_mfma_f32_16x16x32_bf16 v[4:7], v[176:179], v[216:219], v[4:7]
	v_mfma_f32_16x16x32_bf16 v[0:3], v[184:187], v[216:219], v[0:3]
	s_setprio 0
	s_barrier
	s_add_i32 s82, 0, 0x18000
	s_add_i32 s83, 0, 0x1c000
	v_add_u32_e32 v140, s82, v166
	v_add_u32_e32 v152, s83, v166
	ds_read_b128 v[128:131], v140
	ds_read_b128 v[132:135], v140 offset:1024
	ds_read_b128 v[136:139], v140 offset:2048
	ds_read_b128 v[140:143], v140 offset:3072
	ds_read_b128 v[172:175], v152
	ds_read_b128 v[176:179], v152 offset:1024
	ds_read_b128 v[180:183], v152 offset:2048
	ds_read_b128 v[184:187], v152 offset:3072
	s_add_u32 s50, s50, 0x40000
	s_addc_u32 s51, s51, 0
	s_mov_b32 m0, s59
	v_lshl_add_u64 v[226:227], s[50:51], 0, v[150:151]
	ds_read_b128 v[188:191], v169 offset:32768
	ds_read_b128 v[192:195], v169 offset:33792
	ds_read_b128 v[196:199], v169 offset:34816
	ds_read_b128 v[200:203], v169 offset:35840
	ds_read_b128 v[204:207], v169 offset:36864
	ds_read_b128 v[208:211], v169 offset:37888
	ds_read_b128 v[212:215], v169 offset:38912
	ds_read_b128 v[216:219], v169 offset:39936
	global_load_lds_dwordx4 v[226:227], off
	s_mov_b32 m0, s60
	v_lshl_add_u64 v[226:227], s[50:51], 0, v[146:147]
	global_load_lds_dwordx4 v[226:227], off
	s_waitcnt vmcnt(8)
	s_waitcnt lgkmcnt(0)
	s_barrier
	s_setprio 1
	v_mfma_f32_16x16x32_bf16 v[124:127], v[128:131], v[188:191], v[124:127]
	v_mfma_f32_16x16x32_bf16 v[120:123], v[136:139], v[188:191], v[120:123]
	v_mfma_f32_16x16x32_bf16 v[116:119], v[128:131], v[196:199], v[116:119]
	v_mfma_f32_16x16x32_bf16 v[112:115], v[136:139], v[196:199], v[112:115]
	v_mfma_f32_16x16x32_bf16 v[108:111], v[128:131], v[204:207], v[108:111]
	v_mfma_f32_16x16x32_bf16 v[96:99], v[136:139], v[204:207], v[96:99]
	v_mfma_f32_16x16x32_bf16 v[80:83], v[128:131], v[212:215], v[80:83]
	v_mfma_f32_16x16x32_bf16 v[72:75], v[136:139], v[212:215], v[72:75]
	v_mfma_f32_16x16x32_bf16 v[124:127], v[132:135], v[192:195], v[124:127]
	v_mfma_f32_16x16x32_bf16 v[120:123], v[140:143], v[192:195], v[120:123]
	v_mfma_f32_16x16x32_bf16 v[116:119], v[132:135], v[200:203], v[116:119]
	v_mfma_f32_16x16x32_bf16 v[112:115], v[140:143], v[200:203], v[112:115]
	v_mfma_f32_16x16x32_bf16 v[108:111], v[132:135], v[208:211], v[108:111]
	v_mfma_f32_16x16x32_bf16 v[96:99], v[140:143], v[208:211], v[96:99]
	v_mfma_f32_16x16x32_bf16 v[80:83], v[132:135], v[216:219], v[80:83]
	v_mfma_f32_16x16x32_bf16 v[72:75], v[140:143], v[216:219], v[72:75]
	v_mfma_f32_16x16x32_bf16 v[104:107], v[172:175], v[188:191], v[104:107]
	v_mfma_f32_16x16x32_bf16 v[100:103], v[180:183], v[188:191], v[100:103]
	v_mfma_f32_16x16x32_bf16 v[92:95], v[172:175], v[196:199], v[92:95]
	v_mfma_f32_16x16x32_bf16 v[88:91], v[180:183], v[196:199], v[88:91]
	v_mfma_f32_16x16x32_bf16 v[84:87], v[172:175], v[204:207], v[84:87]
	v_mfma_f32_16x16x32_bf16 v[76:79], v[180:183], v[204:207], v[76:79]
	v_mfma_f32_16x16x32_bf16 v[68:71], v[172:175], v[212:215], v[68:71]
	v_mfma_f32_16x16x32_bf16 v[64:67], v[180:183], v[212:215], v[64:67]
	v_mfma_f32_16x16x32_bf16 v[104:107], v[176:179], v[192:195], v[104:107]
	v_mfma_f32_16x16x32_bf16 v[100:103], v[184:187], v[192:195], v[100:103]
	v_mfma_f32_16x16x32_bf16 v[92:95], v[176:179], v[200:203], v[92:95]
	v_mfma_f32_16x16x32_bf16 v[88:91], v[184:187], v[200:203], v[88:91]
	v_mfma_f32_16x16x32_bf16 v[84:87], v[176:179], v[208:211], v[84:87]
	v_mfma_f32_16x16x32_bf16 v[76:79], v[184:187], v[208:211], v[76:79]
	v_mfma_f32_16x16x32_bf16 v[68:71], v[176:179], v[216:219], v[68:71]
	v_mfma_f32_16x16x32_bf16 v[64:67], v[184:187], v[216:219], v[64:67]
	s_setprio 0
	s_barrier
; #define PG8_STAGE(bufoff, gbase, voff) do { _Pragma("unroll") for (int _i = 0; _i < 2; ++_i) \
;         __builtin_amdgcn_global_load_lds((const unsigned*)((const char*)(gbase) + (voff)[_i]), (LAS unsigned*)(lds + (bufoff) + ldsw + _i * 8192), 16, 0, 0); } while (0)
; #define PG8_LDA(dst, b, h) do { _Pragma("unroll") for (int m = 0; m < 4; ++m) _Pragma("unroll") for (int k = 0; k < 2; ++k) dst[m][k] = *(const LAS bf16x8*)(lds + PG8_SA(b, h) + aoff + m * 2048 + k * 1024); } while (0)
; #define PG8_MMA(ai, bj, At, Bt) do { __builtin_amdgcn_s_setprio(1); _Pragma("unroll") for (int m = 0; m < 4; ++m) _Pragma("unroll") for (int n = 0; n < 2; ++n) _Pragma("unroll") for (int k = 0; k < 2; ++k) \
;         acc[ai][bj][m][n] = __builtin_amdgcn_mfma_f32_16x16x32_bf16(Bt[n][k], At[m][k], acc[ai][bj][m][n], 0, 0, 0); __builtin_amdgcn_s_setprio(0); } while (0)
; #define PG8_WAIT_V(n) asm volatile("s_waitcnt vmcnt(" #n ")" ::: "memory")
; #define PG8_WAIT_L(n) asm volatile("s_waitcnt lgkmcnt(" #n ")" ::: "memory")
; #define PG8_BAR __builtin_amdgcn_s_barrier()
; #define PG8_SCHED __builtin_amdgcn_sched_barrier(0)
; template <class Epi, class Sched>
; __device__ __forceinline__ void gemm_phase(LAS unsigned char* lds, const Gemm g, const Sched& S, const Epi& E, const int wid) {
;     ...
;             PG8_LDA(At, 1, 1); PG8_STAGE(PG8_SB(1, 0), b3, voffB); PG8_STAGE(PG8_SB(1, 1), b3 + hstepB, voffB); PG8_STAGE(PG8_SA(1, 0), a3, voffA);
;             PG8_WAIT_V(8); PG8_WAIT_L(0); PG8_BAR; PG8_MMA(1, 0, At, B0); PG8_MMA(1, 1, At, B1); PG8_BAR; PG8_SCHED;
;         }
;         if (wr == 0) PG8_BAR;
	s_add_i32 s50, s82, s54
	v_lshl_add_u64 v[164:165], v[164:165], 0, s[16:17]
	s_mov_b32 m0, s50
	ds_read_b128 v[188:191], v169 offset:49152
	ds_read_b128 v[192:195], v169 offset:50176
	ds_read_b128 v[196:199], v169 offset:51200
	ds_read_b128 v[200:203], v169 offset:52224
	ds_read_b128 v[204:207], v169 offset:53248
	ds_read_b128 v[208:211], v169 offset:54272
	ds_read_b128 v[212:215], v169 offset:55296
	ds_read_b128 v[216:219], v169 offset:56320
	global_load_lds_dwordx4 v[164:165], off
	s_add_i32 m0, s50, 0x2000
	s_add_u32 s48, s48, 0x40080
	v_lshl_add_u64 v[164:165], v[220:221], 0, s[16:17]
	s_addc_u32 s49, s49, 0
	s_add_i32 s50, s83, s54
	global_load_lds_dwordx4 v[164:165], off
	s_mov_b32 m0, s50
	v_lshl_add_u64 v[164:165], s[48:49], 0, v[148:149]
	global_load_lds_dwordx4 v[164:165], off
	s_add_i32 m0, s50, 0x2000
	v_lshl_add_u64 v[164:165], s[48:49], 0, v[144:145]
	global_load_lds_dwordx4 v[164:165], off
	s_mov_b32 m0, s66
	v_lshl_add_u64 v[164:165], v[222:223], 0, s[16:17]
	global_load_lds_dwordx4 v[164:165], off
	s_mov_b32 m0, s67
	v_lshl_add_u64 v[164:165], v[224:225], 0, s[16:17]
	global_load_lds_dwordx4 v[164:165], off
	s_waitcnt vmcnt(8)
	s_waitcnt lgkmcnt(0)
	s_barrier
	s_setprio 1
	v_mfma_f32_16x16x32_bf16 v[60:63], v[128:131], v[188:191], v[60:63]
	v_mfma_f32_16x16x32_bf16 v[56:59], v[136:139], v[188:191], v[56:59]
	v_mfma_f32_16x16x32_bf16 v[48:51], v[128:131], v[196:199], v[48:51]
	v_mfma_f32_16x16x32_bf16 v[40:43], v[136:139], v[196:199], v[40:43]
	v_mfma_f32_16x16x32_bf16 v[32:35], v[128:131], v[204:207], v[32:35]
	v_mfma_f32_16x16x32_bf16 v[24:27], v[136:139], v[204:207], v[24:27]
	v_mfma_f32_16x16x32_bf16 v[16:19], v[128:131], v[212:215], v[16:19]
	v_mfma_f32_16x16x32_bf16 v[8:11], v[136:139], v[212:215], v[8:11]
	v_mfma_f32_16x16x32_bf16 v[60:63], v[132:135], v[192:195], v[60:63]
	v_mfma_f32_16x16x32_bf16 v[56:59], v[140:143], v[192:195], v[56:59]
	v_mfma_f32_16x16x32_bf16 v[48:51], v[132:135], v[200:203], v[48:51]
	v_mfma_f32_16x16x32_bf16 v[40:43], v[140:143], v[200:203], v[40:43]
	v_mfma_f32_16x16x32_bf16 v[32:35], v[132:135], v[208:211], v[32:35]
	v_mfma_f32_16x16x32_bf16 v[24:27], v[140:143], v[208:211], v[24:27]
	v_mfma_f32_16x16x32_bf16 v[16:19], v[132:135], v[216:219], v[16:19]
	v_mfma_f32_16x16x32_bf16 v[8:11], v[140:143], v[216:219], v[8:11]
	v_mfma_f32_16x16x32_bf16 v[52:55], v[172:175], v[188:191], v[52:55]
	v_mfma_f32_16x16x32_bf16 v[44:47], v[180:183], v[188:191], v[44:47]
	v_mfma_f32_16x16x32_bf16 v[36:39], v[172:175], v[196:199], v[36:39]
	v_mfma_f32_16x16x32_bf16 v[28:31], v[180:183], v[196:199], v[28:31]
	v_mfma_f32_16x16x32_bf16 v[20:23], v[172:175], v[204:207], v[20:23]
	v_mfma_f32_16x16x32_bf16 v[12:15], v[180:183], v[204:207], v[12:15]
	v_mfma_f32_16x16x32_bf16 v[4:7], v[172:175], v[212:215], v[4:7]
	v_mfma_f32_16x16x32_bf16 v[0:3], v[180:183], v[212:215], v[0:3]
	v_mfma_f32_16x16x32_bf16 v[52:55], v[176:179], v[192:195], v[52:55]
	v_mfma_f32_16x16x32_bf16 v[44:47], v[184:187], v[192:195], v[44:47]
	v_mfma_f32_16x16x32_bf16 v[36:39], v[176:179], v[200:203], v[36:39]
	v_mfma_f32_16x16x32_bf16 v[28:31], v[184:187], v[200:203], v[28:31]
	v_mfma_f32_16x16x32_bf16 v[20:23], v[176:179], v[208:211], v[20:23]
	v_mfma_f32_16x16x32_bf16 v[12:15], v[184:187], v[208:211], v[12:15]
	v_mfma_f32_16x16x32_bf16 v[4:7], v[176:179], v[216:219], v[4:7]
	v_mfma_f32_16x16x32_bf16 v[0:3], v[184:187], v[216:219], v[0:3]
	s_setprio 0
	s_barrier
	s_add_i32 s81, s81, 2
	s_add_u32 s46, s46, 0x100
	s_addc_u32 s47, s47, 0
	s_add_u32 s79, s79, 0x100
	s_addc_u32 s80, s80, 0
	s_cmp_gt_u32 s81, 13
	s_cbranch_scc0 .LBB0_546
	s_and_b64 vcc, exec, s[18:19]
	s_cbranch_vccz .LBB0_549
	s_barrier

; #define PG8_STAGE(bufoff, gbase, voff) do { _Pragma("unroll") for (int _i = 0; _i < 2; ++_i) \
;         __builtin_amdgcn_global_load_lds((const unsigned*)((const char*)(gbase) + (voff)[_i]), (LAS unsigned*)(lds + (bufoff) + ldsw + _i * 8192), 16, 0, 0); } while (0)
; #define PG8_LDA(dst, b, h) do { _Pragma("unroll") for (int m = 0; m < 4; ++m) _Pragma("unroll") for (int k = 0; k < 2; ++k) dst[m][k] = *(const LAS bf16x8*)(lds + PG8_SA(b, h) + aoff + m * 2048 + k * 1024); } while (0)
; #define PG8_LDB(dst, b, h) do { _Pragma("unroll") for (int n = 0; n < 2; ++n) _Pragma("unroll") for (int k = 0; k < 2; ++k) dst[n][k] = *(const LAS bf16x8*)(lds + PG8_SB(b, h) + boff + n * 2048 + k * 1024); } while (0)
; #define PG8_MMA(ai, bj, At, Bt) do { __builtin_amdgcn_s_setprio(1); _Pragma("unroll") for (int m = 0; m < 4; ++m) _Pragma("unroll") for (int n = 0; n < 2; ++n) _Pragma("unroll") for (int k = 0; k < 2; ++k) \
;         acc[ai][bj][m][n] = __builtin_amdgcn_mfma_f32_16x16x32_bf16(Bt[n][k], At[m][k], acc[ai][bj][m][n], 0, 0, 0); __builtin_amdgcn_s_setprio(0); } while (0)
; #define PG8_WAIT_V(n) asm volatile("s_waitcnt vmcnt(" #n ")" ::: "memory")
; #define PG8_WAIT_L(n) asm volatile("s_waitcnt lgkmcnt(" #n ")" ::: "memory")
; #define PG8_BAR __builtin_amdgcn_s_barrier()
; #define PG8_SCHED __builtin_amdgcn_sched_barrier(0)
; template <class Epi, class Sched>
; __device__ __forceinline__ void gemm_phase(LAS unsigned char* lds, const Gemm g, const Sched& S, const Epi& E, const int wid) {
;     ...
;             const bool last = (t == nt - 2);
;             const char* a1 = cA + (size_t)(t + 1) * kstep;
;             const char* a2 = last ? nA : cA + (size_t)(t + 2) * kstep; const char* b2 = last ? nB : cB + (size_t)(t + 2) * kstep;
;             const char* a3 = a2 + kstep; const char* b3 = b2 + kstep;
;             PG8_LDB(B0, 0, 0); PG8_LDB(B1, 0, 1); PG8_SCHED; PG8_LDA(At, 0, 0); PG8_STAGE(PG8_SA(1, 1), a1 + hstepA, voffA);
;             PG8_WAIT_V(8); PG8_WAIT_L(0); PG8_BAR; PG8_MMA(0, 0, At, B0); PG8_MMA(0, 1, At, B1); PG8_BAR; PG8_SCHED;
;             PG8_LDA(At, 0, 1); PG8_STAGE(PG8_SB(0, 0), b2, voffB); PG8_STAGE(PG8_SB(0, 1), b2 + hstepB, voffB); PG8_STAGE(PG8_SA(0, 0), a2, voffA);
;             PG8_WAIT_V(8); PG8_WAIT_L(0); PG8_BAR; PG8_MMA(1, 0, At, B0); PG8_MMA(1, 1, At, B1); PG8_BAR; PG8_SCHED;
.LBB0_680:
	ds_read_b128 v[128:131], v235
	ds_read_b128 v[132:135], v235 offset:1024
	ds_read_b128 v[136:139], v235 offset:2048
	ds_read_b128 v[140:143], v235 offset:3072
	ds_read_b128 v[144:147], v236
	ds_read_b128 v[148:151], v236 offset:1024
	ds_read_b128 v[152:155], v236 offset:2048
	ds_read_b128 v[156:159], v236 offset:3072
	s_add_u32 s34, s30, 0xfffc0080
	s_addc_u32 s35, s31, -1
	s_cmp_eq_u32 s63, 12
	s_cselect_b32 s37, s21, s35
	s_cselect_b32 s36, s59, s34
	s_cselect_b32 s35, s19, s62
	s_cselect_b32 s34, s60, s61
	v_lshl_add_u64 v[192:193], s[30:31], 0, v[214:215]
	s_add_i32 m0, s44, 0xc000
	ds_read_b128 v[160:163], v237
	ds_read_b128 v[164:167], v237 offset:1024
	ds_read_b128 v[168:171], v237 offset:2048
	ds_read_b128 v[172:175], v237 offset:3072
	ds_read_b128 v[176:179], v237 offset:4096
	ds_read_b128 v[180:183], v237 offset:5120
	ds_read_b128 v[184:187], v237 offset:6144
	ds_read_b128 v[188:191], v237 offset:7168
	global_load_lds_dwordx4 v[192:193], off
	s_add_i32 m0, s44, 0xe000
	v_lshl_add_u64 v[192:193], s[30:31], 0, v[216:217]
	global_load_lds_dwordx4 v[192:193], off
	s_waitcnt vmcnt(8)
	s_waitcnt lgkmcnt(0)
	s_barrier
	s_setprio 1
	v_mfma_f32_16x16x32_bf16 v[124:127], v[128:131], v[160:163], v[124:127]
	v_mfma_f32_16x16x32_bf16 v[120:123], v[136:139], v[160:163], v[120:123]
	v_mfma_f32_16x16x32_bf16 v[112:115], v[128:131], v[168:171], v[112:115]
	v_mfma_f32_16x16x32_bf16 v[104:107], v[136:139], v[168:171], v[104:107]
	v_mfma_f32_16x16x32_bf16 v[96:99], v[128:131], v[176:179], v[96:99]
	v_mfma_f32_16x16x32_bf16 v[88:91], v[136:139], v[176:179], v[88:91]
	v_mfma_f32_16x16x32_bf16 v[76:79], v[128:131], v[184:187], v[76:79]
	v_mfma_f32_16x16x32_bf16 v[72:75], v[136:139], v[184:187], v[72:75]
	v_mfma_f32_16x16x32_bf16 v[124:127], v[132:135], v[164:167], v[124:127]
	v_mfma_f32_16x16x32_bf16 v[120:123], v[140:143], v[164:167], v[120:123]
	v_mfma_f32_16x16x32_bf16 v[112:115], v[132:135], v[172:175], v[112:115]
	v_mfma_f32_16x16x32_bf16 v[104:107], v[140:143], v[172:175], v[104:107]
	v_mfma_f32_16x16x32_bf16 v[96:99], v[132:135], v[180:183], v[96:99]
	v_mfma_f32_16x16x32_bf16 v[88:91], v[140:143], v[180:183], v[88:91]
	v_mfma_f32_16x16x32_bf16 v[76:79], v[132:135], v[188:191], v[76:79]
	v_mfma_f32_16x16x32_bf16 v[72:75], v[140:143], v[188:191], v[72:75]
	v_mfma_f32_16x16x32_bf16 v[116:119], v[144:147], v[160:163], v[116:119]
	v_mfma_f32_16x16x32_bf16 v[108:111], v[152:155], v[160:163], v[108:111]
	v_mfma_f32_16x16x32_bf16 v[100:103], v[144:147], v[168:171], v[100:103]
	v_mfma_f32_16x16x32_bf16 v[92:95], v[152:155], v[168:171], v[92:95]
	v_mfma_f32_16x16x32_bf16 v[84:87], v[144:147], v[176:179], v[84:87]
	v_mfma_f32_16x16x32_bf16 v[80:83], v[152:155], v[176:179], v[80:83]
	v_mfma_f32_16x16x32_bf16 v[68:71], v[144:147], v[184:187], v[68:71]
	v_mfma_f32_16x16x32_bf16 v[64:67], v[152:155], v[184:187], v[64:67]
	v_mfma_f32_16x16x32_bf16 v[116:119], v[148:151], v[164:167], v[116:119]
	v_mfma_f32_16x16x32_bf16 v[108:111], v[156:159], v[164:167], v[108:111]
	v_mfma_f32_16x16x32_bf16 v[100:103], v[148:151], v[172:175], v[100:103]
	v_mfma_f32_16x16x32_bf16 v[92:95], v[156:159], v[172:175], v[92:95]
	v_mfma_f32_16x16x32_bf16 v[84:87], v[148:151], v[180:183], v[84:87]
	v_mfma_f32_16x16x32_bf16 v[80:83], v[156:159], v[180:183], v[80:83]
	v_mfma_f32_16x16x32_bf16 v[68:71], v[148:151], v[188:191], v[68:71]
	v_mfma_f32_16x16x32_bf16 v[64:67], v[156:159], v[188:191], v[64:67]
	s_setprio 0
	s_barrier
	s_add_i32 s64, s51, s41
	v_lshl_add_u64 v[192:193], s[34:35], 0, v[210:211]
	s_mov_b32 m0, s64
	ds_read_b128 v[160:163], v237 offset:16384
	ds_read_b128 v[164:167], v237 offset:17408
	ds_read_b128 v[168:171], v237 offset:18432
	ds_read_b128 v[172:175], v237 offset:19456
	ds_read_b128 v[176:179], v237 offset:20480
	ds_read_b128 v[180:183], v237 offset:21504
	ds_read_b128 v[184:187], v237 offset:22528
	ds_read_b128 v[188:191], v237 offset:23552
	global_load_lds_dwordx4 v[192:193], off
	s_add_i32 m0, s64, 0x2000
	s_add_u32 s64, s34, 0x40000
	v_lshl_add_u64 v[194:195], s[34:35], 0, v[208:209]
	s_addc_u32 s65, s35, 0
	s_add_i32 s66, s52, s41
	global_load_lds_dwordx4 v[194:195], off
	v_lshl_add_u64 v[196:197], s[64:65], 0, v[210:211]
	s_mov_b32 m0, s66
	v_lshl_add_u64 v[198:199], s[36:37], 0, v[208:209]
	global_load_lds_dwordx4 v[196:197], off
	s_add_i32 m0, s66, 0x2000
	v_lshl_add_u64 v[196:197], s[64:65], 0, v[208:209]
	global_load_lds_dwordx4 v[196:197], off
	s_mov_b32 m0, s44
	v_lshl_add_u64 v[196:197], s[36:37], 0, v[210:211]
	global_load_lds_dwordx4 v[196:197], off
	s_mov_b32 m0, s45
	s_nop 0
	global_load_lds_dwordx4 v[198:199], off
	s_waitcnt vmcnt(8)
	s_waitcnt lgkmcnt(0)
	s_barrier
; #define PG8_STAGE(bufoff, gbase, voff) do { _Pragma("unroll") for (int _i = 0; _i < 2; ++_i) \
;         __builtin_amdgcn_global_load_lds((const unsigned*)((const char*)(gbase) + (voff)[_i]), (LAS unsigned*)(lds + (bufoff) + ldsw + _i * 8192), 16, 0, 0); } while (0)
; #define PG8_LDA(dst, b, h) do { _Pragma("unroll") for (int m = 0; m < 4; ++m) _Pragma("unroll") for (int k = 0; k < 2; ++k) dst[m][k] = *(const LAS bf16x8*)(lds + PG8_SA(b, h) + aoff + m * 2048 + k * 1024); } while (0)
; #define PG8_LDB(dst, b, h) do { _Pragma("unroll") for (int n = 0; n < 2; ++n) _Pragma("unroll") for (int k = 0; k < 2; ++k) dst[n][k] = *(const LAS bf16x8*)(lds + PG8_SB(b, h) + boff + n * 2048 + k * 1024); } while (0)
; #define PG8_MMA(ai, bj, At, Bt) do { __builtin_amdgcn_s_setprio(1); _Pragma("unroll") for (int m = 0; m < 4; ++m) _Pragma("unroll") for (int n = 0; n < 2; ++n) _Pragma("unroll") for (int k = 0; k < 2; ++k) \
;         acc[ai][bj][m][n] = __builtin_amdgcn_mfma_f32_16x16x32_bf16(Bt[n][k], At[m][k], acc[ai][bj][m][n], 0, 0, 0); __builtin_amdgcn_s_setprio(0); } while (0)
; #define PG8_WAIT_V(n) asm volatile("s_waitcnt vmcnt(" #n ")" ::: "memory")
; #define PG8_WAIT_L(n) asm volatile("s_waitcnt lgkmcnt(" #n ")" ::: "memory")
; #define PG8_BAR __builtin_amdgcn_s_barrier()
; #define PG8_SCHED __builtin_amdgcn_sched_barrier(0)
; template <class Epi, class Sched>
; __device__ __forceinline__ void gemm_phase(LAS unsigned char* lds, const Gemm g, const Sched& S, const Epi& E, const int wid) {
;     ...
;             PG8_WAIT_V(8); PG8_WAIT_L(0); PG8_BAR; PG8_MMA(1, 0, At, B0); PG8_MMA(1, 1, At, B1); PG8_BAR; PG8_SCHED;
;             PG8_LDB(B0, 1, 0); PG8_LDB(B1, 1, 1); PG8_SCHED; PG8_LDA(At, 1, 0); PG8_STAGE(PG8_SA(0, 1), a2 + hstepA, voffA);
;             PG8_WAIT_V(8); PG8_WAIT_L(0); PG8_BAR; PG8_MMA(0, 0, At, B0); PG8_MMA(0, 1, At, B1); PG8_BAR; PG8_SCHED;
	s_setprio 1
	v_mfma_f32_16x16x32_bf16 v[60:63], v[128:131], v[160:163], v[60:63]
	v_mfma_f32_16x16x32_bf16 v[56:59], v[136:139], v[160:163], v[56:59]
	v_mfma_f32_16x16x32_bf16 v[48:51], v[128:131], v[168:171], v[48:51]
	v_mfma_f32_16x16x32_bf16 v[40:43], v[136:139], v[168:171], v[40:43]
	v_mfma_f32_16x16x32_bf16 v[32:35], v[128:131], v[176:179], v[32:35]
	v_mfma_f32_16x16x32_bf16 v[24:27], v[136:139], v[176:179], v[24:27]
	v_mfma_f32_16x16x32_bf16 v[12:15], v[128:131], v[184:187], v[12:15]
	v_mfma_f32_16x16x32_bf16 v[8:11], v[136:139], v[184:187], v[8:11]
	v_mfma_f32_16x16x32_bf16 v[60:63], v[132:135], v[164:167], v[60:63]
	v_mfma_f32_16x16x32_bf16 v[56:59], v[140:143], v[164:167], v[56:59]
	v_mfma_f32_16x16x32_bf16 v[48:51], v[132:135], v[172:175], v[48:51]
	v_mfma_f32_16x16x32_bf16 v[40:43], v[140:143], v[172:175], v[40:43]
	v_mfma_f32_16x16x32_bf16 v[32:35], v[132:135], v[180:183], v[32:35]
	v_mfma_f32_16x16x32_bf16 v[24:27], v[140:143], v[180:183], v[24:27]
	v_mfma_f32_16x16x32_bf16 v[12:15], v[132:135], v[188:191], v[12:15]
	v_mfma_f32_16x16x32_bf16 v[8:11], v[140:143], v[188:191], v[8:11]
	v_mfma_f32_16x16x32_bf16 v[52:55], v[144:147], v[160:163], v[52:55]
	v_mfma_f32_16x16x32_bf16 v[44:47], v[152:155], v[160:163], v[44:47]
	v_mfma_f32_16x16x32_bf16 v[36:39], v[144:147], v[168:171], v[36:39]
	v_mfma_f32_16x16x32_bf16 v[28:31], v[152:155], v[168:171], v[28:31]
	v_mfma_f32_16x16x32_bf16 v[20:23], v[144:147], v[176:179], v[20:23]
	v_mfma_f32_16x16x32_bf16 v[16:19], v[152:155], v[176:179], v[16:19]
	v_mfma_f32_16x16x32_bf16 v[4:7], v[144:147], v[184:187], v[4:7]
	v_mfma_f32_16x16x32_bf16 v[0:3], v[152:155], v[184:187], v[0:3]
	v_mfma_f32_16x16x32_bf16 v[52:55], v[148:151], v[164:167], v[52:55]
	v_mfma_f32_16x16x32_bf16 v[44:47], v[156:159], v[164:167], v[44:47]
	v_mfma_f32_16x16x32_bf16 v[36:39], v[148:151], v[172:175], v[36:39]
	v_mfma_f32_16x16x32_bf16 v[28:31], v[156:159], v[172:175], v[28:31]
	v_mfma_f32_16x16x32_bf16 v[20:23], v[148:151], v[180:183], v[20:23]
	v_mfma_f32_16x16x32_bf16 v[16:19], v[156:159], v[180:183], v[16:19]
	v_mfma_f32_16x16x32_bf16 v[4:7], v[148:151], v[188:191], v[4:7]
	v_mfma_f32_16x16x32_bf16 v[0:3], v[156:159], v[188:191], v[0:3]
	s_setprio 0
	s_barrier
	s_add_i32 s64, 0, 0x18000
	s_add_i32 s65, 0, 0x1c000
	v_add_u32_e32 v140, s64, v233
	v_add_u32_e32 v156, s65, v233
	ds_read_b128 v[128:131], v140
	ds_read_b128 v[132:135], v140 offset:1024
	ds_read_b128 v[136:139], v140 offset:2048
	ds_read_b128 v[140:143], v140 offset:3072
	ds_read_b128 v[144:147], v156
	ds_read_b128 v[148:151], v156 offset:1024
	ds_read_b128 v[152:155], v156 offset:2048
	ds_read_b128 v[156:159], v156 offset:3072
	s_add_u32 s36, s36, 0x40000
	s_addc_u32 s37, s37, 0
	s_mov_b32 m0, s46
	v_lshl_add_u64 v[200:201], s[36:37], 0, v[210:211]
	ds_read_b128 v[160:163], v237 offset:32768
	ds_read_b128 v[164:167], v237 offset:33792
	ds_read_b128 v[168:171], v237 offset:34816
	ds_read_b128 v[172:175], v237 offset:35840
	ds_read_b128 v[176:179], v237 offset:36864
	ds_read_b128 v[180:183], v237 offset:37888
	ds_read_b128 v[184:187], v237 offset:38912
	ds_read_b128 v[188:191], v237 offset:39936
	global_load_lds_dwordx4 v[200:201], off
	s_mov_b32 m0, s47
	v_lshl_add_u64 v[200:201], s[36:37], 0, v[208:209]
	global_load_lds_dwordx4 v[200:201], off
	s_waitcnt vmcnt(8)
	s_waitcnt lgkmcnt(0)
	s_barrier
	s_setprio 1
	v_mfma_f32_16x16x32_bf16 v[124:127], v[128:131], v[160:163], v[124:127]
	v_mfma_f32_16x16x32_bf16 v[120:123], v[136:139], v[160:163], v[120:123]
	v_mfma_f32_16x16x32_bf16 v[112:115], v[128:131], v[168:171], v[112:115]
	v_mfma_f32_16x16x32_bf16 v[104:107], v[136:139], v[168:171], v[104:107]
	v_mfma_f32_16x16x32_bf16 v[96:99], v[128:131], v[176:179], v[96:99]
	v_mfma_f32_16x16x32_bf16 v[88:91], v[136:139], v[176:179], v[88:91]
	v_mfma_f32_16x16x32_bf16 v[76:79], v[128:131], v[184:187], v[76:79]
	v_mfma_f32_16x16x32_bf16 v[72:75], v[136:139], v[184:187], v[72:75]
	v_mfma_f32_16x16x32_bf16 v[124:127], v[132:135], v[164:167], v[124:127]
	v_mfma_f32_16x16x32_bf16 v[120:123], v[140:143], v[164:167], v[120:123]
	v_mfma_f32_16x16x32_bf16 v[112:115], v[132:135], v[172:175], v[112:115]
	v_mfma_f32_16x16x32_bf16 v[104:107], v[140:143], v[172:175], v[104:107]
	v_mfma_f32_16x16x32_bf16 v[96:99], v[132:135], v[180:183], v[96:99]
	v_mfma_f32_16x16x32_bf16 v[88:91], v[140:143], v[180:183], v[88:91]
	v_mfma_f32_16x16x32_bf16 v[76:79], v[132:135], v[188:191], v[76:79]
	v_mfma_f32_16x16x32_bf16 v[72:75], v[140:143], v[188:191], v[72:75]
	v_mfma_f32_16x16x32_bf16 v[116:119], v[144:147], v[160:163], v[116:119]
	v_mfma_f32_16x16x32_bf16 v[108:111], v[152:155], v[160:163], v[108:111]
	v_mfma_f32_16x16x32_bf16 v[100:103], v[144:147], v[168:171], v[100:103]
	v_mfma_f32_16x16x32_bf16 v[92:95], v[152:155], v[168:171], v[92:95]
	v_mfma_f32_16x16x32_bf16 v[84:87], v[144:147], v[176:179], v[84:87]
	v_mfma_f32_16x16x32_bf16 v[80:83], v[152:155], v[176:179], v[80:83]
	v_mfma_f32_16x16x32_bf16 v[68:71], v[144:147], v[184:187], v[68:71]
	v_mfma_f32_16x16x32_bf16 v[64:67], v[152:155], v[184:187], v[64:67]
	v_mfma_f32_16x16x32_bf16 v[116:119], v[148:151], v[164:167], v[116:119]
	v_mfma_f32_16x16x32_bf16 v[108:111], v[156:159], v[164:167], v[108:111]
	v_mfma_f32_16x16x32_bf16 v[100:103], v[148:151], v[172:175], v[100:103]
	v_mfma_f32_16x16x32_bf16 v[92:95], v[156:159], v[172:175], v[92:95]
	v_mfma_f32_16x16x32_bf16 v[84:87], v[148:151], v[180:183], v[84:87]
	v_mfma_f32_16x16x32_bf16 v[80:83], v[156:159], v[180:183], v[80:83]
	v_mfma_f32_16x16x32_bf16 v[68:71], v[148:151], v[188:191], v[68:71]
	v_mfma_f32_16x16x32_bf16 v[64:67], v[156:159], v[188:191], v[64:67]
	s_setprio 0
	s_barrier
; #define PG8_STAGE(bufoff, gbase, voff) do { _Pragma("unroll") for (int _i = 0; _i < 2; ++_i) \
;         __builtin_amdgcn_global_load_lds((const unsigned*)((const char*)(gbase) + (voff)[_i]), (LAS unsigned*)(lds + (bufoff) + ldsw + _i * 8192), 16, 0, 0); } while (0)
; #define PG8_LDA(dst, b, h) do { _Pragma("unroll") for (int m = 0; m < 4; ++m) _Pragma("unroll") for (int k = 0; k < 2; ++k) dst[m][k] = *(const LAS bf16x8*)(lds + PG8_SA(b, h) + aoff + m * 2048 + k * 1024); } while (0)
; #define PG8_MMA(ai, bj, At, Bt) do { __builtin_amdgcn_s_setprio(1); _Pragma("unroll") for (int m = 0; m < 4; ++m) _Pragma("unroll") for (int n = 0; n < 2; ++n) _Pragma("unroll") for (int k = 0; k < 2; ++k) \
;         acc[ai][bj][m][n] = __builtin_amdgcn_mfma_f32_16x16x32_bf16(Bt[n][k], At[m][k], acc[ai][bj][m][n], 0, 0, 0); __builtin_amdgcn_s_setprio(0); } while (0)
; #define PG8_WAIT_V(n) asm volatile("s_waitcnt vmcnt(" #n ")" ::: "memory")
; #define PG8_WAIT_L(n) asm volatile("s_waitcnt lgkmcnt(" #n ")" ::: "memory")
; #define PG8_BAR __builtin_amdgcn_s_barrier()
; #define PG8_SCHED __builtin_amdgcn_sched_barrier(0)
; template <class Epi, class Sched>
; __device__ __forceinline__ void gemm_phase(LAS unsigned char* lds, const Gemm g, const Sched& S, const Epi& E, const int wid) {
;     ...
;             PG8_LDA(At, 1, 1); PG8_STAGE(PG8_SB(1, 0), b3, voffB); PG8_STAGE(PG8_SB(1, 1), b3 + hstepB, voffB); PG8_STAGE(PG8_SA(1, 0), a3, voffA);
;             PG8_WAIT_V(8); PG8_WAIT_L(0); PG8_BAR; PG8_MMA(1, 0, At, B0); PG8_MMA(1, 1, At, B1); PG8_BAR; PG8_SCHED;
;         }
;         if (wr == 0) PG8_BAR;
	s_add_i32 s36, s64, s41
	v_lshl_add_u64 v[192:193], v[192:193], 0, s[12:13]
	s_mov_b32 m0, s36
	ds_read_b128 v[160:163], v237 offset:49152
	ds_read_b128 v[164:167], v237 offset:50176
	ds_read_b128 v[168:171], v237 offset:51200
	ds_read_b128 v[172:175], v237 offset:52224
	ds_read_b128 v[176:179], v237 offset:53248
	ds_read_b128 v[180:183], v237 offset:54272
	ds_read_b128 v[184:187], v237 offset:55296
	ds_read_b128 v[188:191], v237 offset:56320
	global_load_lds_dwordx4 v[192:193], off
	s_add_i32 m0, s36, 0x2000
	s_add_u32 s34, s34, 0x40080
	v_lshl_add_u64 v[192:193], v[194:195], 0, s[12:13]
	s_addc_u32 s35, s35, 0
	s_add_i32 s36, s65, s41
	global_load_lds_dwordx4 v[192:193], off
	s_mov_b32 m0, s36
	v_lshl_add_u64 v[192:193], s[34:35], 0, v[210:211]
	global_load_lds_dwordx4 v[192:193], off
	s_add_i32 m0, s36, 0x2000
	v_lshl_add_u64 v[192:193], s[34:35], 0, v[208:209]
	global_load_lds_dwordx4 v[192:193], off
	s_mov_b32 m0, s33
	v_lshl_add_u64 v[192:193], v[196:197], 0, s[12:13]
	global_load_lds_dwordx4 v[192:193], off
	s_mov_b32 m0, s50
	v_lshl_add_u64 v[192:193], v[198:199], 0, s[12:13]
	global_load_lds_dwordx4 v[192:193], off
	s_waitcnt vmcnt(8)
	s_waitcnt lgkmcnt(0)
	s_barrier
	s_setprio 1
	v_mfma_f32_16x16x32_bf16 v[60:63], v[128:131], v[160:163], v[60:63]
	v_mfma_f32_16x16x32_bf16 v[56:59], v[136:139], v[160:163], v[56:59]
	v_mfma_f32_16x16x32_bf16 v[48:51], v[128:131], v[168:171], v[48:51]
	v_mfma_f32_16x16x32_bf16 v[40:43], v[136:139], v[168:171], v[40:43]
	v_mfma_f32_16x16x32_bf16 v[32:35], v[128:131], v[176:179], v[32:35]
	v_mfma_f32_16x16x32_bf16 v[24:27], v[136:139], v[176:179], v[24:27]
	v_mfma_f32_16x16x32_bf16 v[12:15], v[128:131], v[184:187], v[12:15]
	v_mfma_f32_16x16x32_bf16 v[8:11], v[136:139], v[184:187], v[8:11]
	v_mfma_f32_16x16x32_bf16 v[60:63], v[132:135], v[164:167], v[60:63]
	v_mfma_f32_16x16x32_bf16 v[56:59], v[140:143], v[164:167], v[56:59]
	v_mfma_f32_16x16x32_bf16 v[48:51], v[132:135], v[172:175], v[48:51]
	v_mfma_f32_16x16x32_bf16 v[40:43], v[140:143], v[172:175], v[40:43]
	v_mfma_f32_16x16x32_bf16 v[32:35], v[132:135], v[180:183], v[32:35]
	v_mfma_f32_16x16x32_bf16 v[24:27], v[140:143], v[180:183], v[24:27]
	v_mfma_f32_16x16x32_bf16 v[12:15], v[132:135], v[188:191], v[12:15]
	v_mfma_f32_16x16x32_bf16 v[8:11], v[140:143], v[188:191], v[8:11]
	v_mfma_f32_16x16x32_bf16 v[52:55], v[144:147], v[160:163], v[52:55]
	v_mfma_f32_16x16x32_bf16 v[44:47], v[152:155], v[160:163], v[44:47]
	v_mfma_f32_16x16x32_bf16 v[36:39], v[144:147], v[168:171], v[36:39]
	v_mfma_f32_16x16x32_bf16 v[28:31], v[152:155], v[168:171], v[28:31]
	v_mfma_f32_16x16x32_bf16 v[20:23], v[144:147], v[176:179], v[20:23]
	v_mfma_f32_16x16x32_bf16 v[16:19], v[152:155], v[176:179], v[16:19]
	v_mfma_f32_16x16x32_bf16 v[4:7], v[144:147], v[184:187], v[4:7]
	v_mfma_f32_16x16x32_bf16 v[0:3], v[152:155], v[184:187], v[0:3]
	v_mfma_f32_16x16x32_bf16 v[52:55], v[148:151], v[164:167], v[52:55]
	v_mfma_f32_16x16x32_bf16 v[44:47], v[156:159], v[164:167], v[44:47]
	v_mfma_f32_16x16x32_bf16 v[36:39], v[148:151], v[172:175], v[36:39]
	v_mfma_f32_16x16x32_bf16 v[28:31], v[156:159], v[172:175], v[28:31]
	v_mfma_f32_16x16x32_bf16 v[20:23], v[148:151], v[180:183], v[20:23]
	v_mfma_f32_16x16x32_bf16 v[16:19], v[156:159], v[180:183], v[16:19]
	v_mfma_f32_16x16x32_bf16 v[4:7], v[148:151], v[188:191], v[4:7]
	v_mfma_f32_16x16x32_bf16 v[0:3], v[156:159], v[188:191], v[0:3]
	s_setprio 0
	s_barrier
	s_add_i32 s63, s63, 2
	s_add_u32 s30, s30, 0x100
	s_addc_u32 s31, s31, 0
	s_add_u32 s61, s61, 0x100
	s_addc_u32 s62, s62, 0
	s_cmp_gt_u32 s63, 13
	s_cbranch_scc0 .LBB0_680
	s_and_b64 vcc, exec, s[14:15]
	s_cbranch_vccz .LBB0_683
	s_barrier
